# GEMM K loops: first trip peeled with C operand 0, accumulator clearing blocks removed (six of eight GEMM instances)
# speedup vs baseline: 1.0069x; 1.0069x over previous
; #define PG8_STAGE(bufoff, gbase, voff) do { _Pragma("unroll") for (int _i = 0; _i < 2; ++_i) \
;         __builtin_amdgcn_global_load_lds((const unsigned*)((const char*)(gbase) + (voff)[_i]), (LAS unsigned*)(lds + (bufoff) + ldsw + _i * 8192), 16, 0, 0); } while (0)
; #define PG8_LDA(dst, b, h) do { _Pragma("unroll") for (int m = 0; m < 4; ++m) _Pragma("unroll") for (int k = 0; k < 2; ++k) dst[m][k] = *(const LAS bf16x8*)(lds + PG8_SA(b, h) + aoff + m * 2048 + k * 1024); } while (0)
; #define PG8_LDB(dst, b, h) do { _Pragma("unroll") for (int n = 0; n < 2; ++n) _Pragma("unroll") for (int k = 0; k < 2; ++k) dst[n][k] = *(const LAS bf16x8*)(lds + PG8_SB(b, h) + boff + n * 2048 + k * 1024); } while (0)
; #define PG8_WAIT_V(n) asm volatile("s_waitcnt vmcnt(" #n ")" ::: "memory")
; #define PG8_WAIT_L(n) asm volatile("s_waitcnt lgkmcnt(" #n ")" ::: "memory")
; #define PG8_BAR __builtin_amdgcn_s_barrier()
; #define PG8_SCHED __builtin_amdgcn_sched_barrier(0)
; template <class Epi, class Sched, bool ALIGN_EPI, bool SP2, bool PERMA = false>
; __device__ __forceinline__ void gemm_phase(LAS unsigned char* lds, const int tid, const int lda, const int ldb, const Sched& S, const Epi& E) {
;     ...
;     for (;;) {
;         const bool has_next = S.next(ui + 1, nxt);
;         const char* nA = has_next ? (const char*)nxt.A : cA; const char* nB = has_next ? (const char*)nxt.B : cB;
;         const int nt = cur.nt;
;         for (int t = 0; t < nt; t += 2) {
;             const bool last = (t == nt - 2);
;             const char* a1 = cA + (size_t)(t + 1) * kstep;
;             const char* a2 = last ? nA : cA + (size_t)(t + 2) * kstep; const char* b2 = last ? nB : cB + (size_t)(t + 2) * kstep;
;             const char* a3 = a2 + kstep; const char* b3 = b2 + kstep;
;             if constexpr (SP2) {
;             PG8_LDB(B0, 0, 0); PG8_LDB(B1, 0, 1); PG8_SCHED; PG8_LDA(At, 0, 0); PG8_STAGE(PG8_SA(1, 1), a1 + hsA, voffA);
;             PG8_WAIT_V(8); PG8_WAIT_L(0); PG8_BAR; PG8_MMA(0, 0, At, B0); PG8_MMA(0, 1, At, B1); PG8_BAR; PG8_SCHED;
;             PG8_LDA(At, 0, 1); PG8_STAGE(PG8_SB(0, 0), b2, voffB); PG8_STAGE(PG8_SB(0, 1), b2 + hsB, voffB); PG8_STAGE(PG8_SA(0, 0), a2, voffA);
;             PG8_WAIT_V(8); PG8_WAIT_L(0); PG8_BAR; PG8_MMA(1, 0, At, B0); PG8_MMA(1, 1, At, B1); PG8_BAR; PG8_SCHED;
.LBB0_63:
	s_and_b64 s[2:3], s[0:1], exec
	s_cselect_b32 s33, s7, s19
	s_cselect_b32 s92, s6, s18
	s_cselect_b32 vcc_lo, s95, s21
	s_cselect_b32 vcc_hi, s94, s20
	s_add_i32 s34, s17, -2
	s_add_u32 s2, s20, 0x100
	v_mov_b32_e32 v0, 0
	s_addc_u32 s3, s21, 0
	s_mov_b32 s24, 0
	s_waitcnt vmcnt(0)
	s_add_i32 s35, s24, 2
	s_add_u32 s20, s18, 0x100
	s_addc_u32 s21, s19, 0
	s_add_i32 s60, 0, 0x10000
	s_cmp_eq_u32 s34, s24
	s_cselect_b32 s27, s33, s21
	s_cselect_b32 s26, s92, s20
	s_cselect_b32 s25, vcc_lo, s3
	s_cselect_b32 s24, vcc_hi, s2
	s_add_i32 s61, 0, 0x14000
	s_waitcnt lgkmcnt(0)
	v_add_u32_e32 v140, s60, v197
	v_add_u32_e32 v156, s61, v197
	ds_read_b128 v[128:131], v140
	ds_read_b128 v[132:135], v140 offset:1024
	ds_read_b128 v[136:139], v140 offset:2048
	ds_read_b128 v[140:143], v140 offset:3072
	ds_read_b128 v[144:147], v156
	ds_read_b128 v[148:151], v156 offset:1024
	ds_read_b128 v[152:155], v156 offset:2048
	ds_read_b128 v[156:159], v156 offset:3072
	v_lshl_add_u64 v[208:209], s[18:19], 0, v[164:165]
	s_add_i32 m0, s23, 0xc000
	ds_read_b128 v[166:169], v198
	ds_read_b128 v[170:173], v198 offset:1024
	ds_read_b128 v[174:177], v198 offset:2048
	ds_read_b128 v[178:181], v198 offset:3072
	ds_read_b128 v[182:185], v198 offset:4096
	ds_read_b128 v[186:189], v198 offset:5120
	ds_read_b128 v[200:203], v198 offset:6144
	ds_read_b128 v[204:207], v198 offset:7168
	global_load_lds_dwordx4 v[208:209], off
	v_lshl_add_u64 v[208:209], s[18:19], 0, v[162:163]
	s_add_i32 m0, s23, 0xe000
	s_nop 0
	global_load_lds_dwordx4 v[208:209], off
	s_waitcnt vmcnt(8)
	s_waitcnt lgkmcnt(0)
	s_barrier
	s_setprio 1
	s_waitcnt lgkmcnt(0)
	v_mfma_f32_16x16x32_bf16 v[124:127], v[128:131], v[166:169], 0
	v_mfma_f32_16x16x32_bf16 v[120:123], v[136:139], v[166:169], 0
	v_mfma_f32_16x16x32_bf16 v[116:119], v[128:131], v[174:177], 0
	v_mfma_f32_16x16x32_bf16 v[108:111], v[136:139], v[174:177], 0
	v_mfma_f32_16x16x32_bf16 v[100:103], v[128:131], v[182:185], 0
	v_mfma_f32_16x16x32_bf16 v[92:95], v[136:139], v[182:185], 0
	v_mfma_f32_16x16x32_bf16 v[84:87], v[128:131], v[200:203], 0
	v_mfma_f32_16x16x32_bf16 v[76:79], v[136:139], v[200:203], 0
	v_mfma_f32_16x16x32_bf16 v[124:127], v[132:135], v[170:173], v[124:127]
	v_mfma_f32_16x16x32_bf16 v[120:123], v[140:143], v[170:173], v[120:123]
	v_mfma_f32_16x16x32_bf16 v[116:119], v[132:135], v[178:181], v[116:119]
	v_mfma_f32_16x16x32_bf16 v[108:111], v[140:143], v[178:181], v[108:111]
	v_mfma_f32_16x16x32_bf16 v[100:103], v[132:135], v[186:189], v[100:103]
	v_mfma_f32_16x16x32_bf16 v[92:95], v[140:143], v[186:189], v[92:95]
	v_mfma_f32_16x16x32_bf16 v[84:87], v[132:135], v[204:207], v[84:87]
	v_mfma_f32_16x16x32_bf16 v[76:79], v[140:143], v[204:207], v[76:79]
	s_setprio 0
	s_setprio 1
	v_mfma_f32_16x16x32_bf16 v[112:115], v[144:147], v[166:169], 0
	v_mfma_f32_16x16x32_bf16 v[104:107], v[152:155], v[166:169], 0
	v_mfma_f32_16x16x32_bf16 v[96:99], v[144:147], v[174:177], 0
	v_mfma_f32_16x16x32_bf16 v[88:91], v[152:155], v[174:177], 0
	v_mfma_f32_16x16x32_bf16 v[80:83], v[144:147], v[182:185], 0
	v_mfma_f32_16x16x32_bf16 v[72:75], v[152:155], v[182:185], 0
	v_mfma_f32_16x16x32_bf16 v[68:71], v[144:147], v[200:203], 0
	v_mfma_f32_16x16x32_bf16 v[64:67], v[152:155], v[200:203], 0
	v_mfma_f32_16x16x32_bf16 v[112:115], v[148:151], v[170:173], v[112:115]
	v_mfma_f32_16x16x32_bf16 v[104:107], v[156:159], v[170:173], v[104:107]
	v_mfma_f32_16x16x32_bf16 v[96:99], v[148:151], v[178:181], v[96:99]
	v_mfma_f32_16x16x32_bf16 v[88:91], v[156:159], v[178:181], v[88:91]
	v_mfma_f32_16x16x32_bf16 v[80:83], v[148:151], v[186:189], v[80:83]
	v_mfma_f32_16x16x32_bf16 v[72:75], v[156:159], v[186:189], v[72:75]
	v_mfma_f32_16x16x32_bf16 v[68:71], v[148:151], v[204:207], v[68:71]
	v_mfma_f32_16x16x32_bf16 v[64:67], v[156:159], v[204:207], v[64:67]
	s_setprio 0
	s_barrier
	s_add_i32 s18, s60, s22
	v_lshl_add_u64 v[208:209], s[24:25], 0, v[192:193]
	s_mov_b32 m0, s18
	ds_read_b128 v[166:169], v198 offset:16384
	ds_read_b128 v[170:173], v198 offset:17408
	ds_read_b128 v[174:177], v198 offset:18432
	ds_read_b128 v[178:181], v198 offset:19456
	ds_read_b128 v[182:185], v198 offset:20480
	ds_read_b128 v[186:189], v198 offset:21504
	ds_read_b128 v[200:203], v198 offset:22528
	ds_read_b128 v[204:207], v198 offset:23552
	global_load_lds_dwordx4 v[208:209], off
	s_add_i32 m0, s18, 0x2000
	s_add_u32 s18, s24, 0xb0000
	v_lshl_add_u64 v[210:211], s[24:25], 0, v[160:161]
	s_addc_u32 s19, s25, 0
	s_add_i32 s60, s61, s22
	global_load_lds_dwordx4 v[210:211], off
	v_lshl_add_u64 v[212:213], s[18:19], 0, v[192:193]
	s_mov_b32 m0, s60
	v_lshl_add_u64 v[214:215], s[26:27], 0, v[160:161]
	global_load_lds_dwordx4 v[212:213], off
	v_lshl_add_u64 v[212:213], s[18:19], 0, v[160:161]
	s_add_i32 m0, s60, 0x2000
	s_nop 0
	global_load_lds_dwordx4 v[212:213], off
	v_lshl_add_u64 v[212:213], s[26:27], 0, v[192:193]
	s_mov_b32 m0, s23
	s_nop 0
	global_load_lds_dwordx4 v[212:213], off
	s_mov_b32 m0, s28
	s_nop 0
	global_load_lds_dwordx4 v[214:215], off
	s_waitcnt vmcnt(8)
	s_waitcnt lgkmcnt(0)
	s_barrier
; #define PG8_STAGE(bufoff, gbase, voff) do { _Pragma("unroll") for (int _i = 0; _i < 2; ++_i) \
;         __builtin_amdgcn_global_load_lds((const unsigned*)((const char*)(gbase) + (voff)[_i]), (LAS unsigned*)(lds + (bufoff) + ldsw + _i * 8192), 16, 0, 0); } while (0)
; #define PG8_LDA(dst, b, h) do { _Pragma("unroll") for (int m = 0; m < 4; ++m) _Pragma("unroll") for (int k = 0; k < 2; ++k) dst[m][k] = *(const LAS bf16x8*)(lds + PG8_SA(b, h) + aoff + m * 2048 + k * 1024); } while (0)
; #define PG8_LDB(dst, b, h) do { _Pragma("unroll") for (int n = 0; n < 2; ++n) _Pragma("unroll") for (int k = 0; k < 2; ++k) dst[n][k] = *(const LAS bf16x8*)(lds + PG8_SB(b, h) + boff + n * 2048 + k * 1024); } while (0)
; #define PG8_MMA(ai, bj, At, Bt) do { __builtin_amdgcn_s_setprio(1); _Pragma("unroll") for (int m = 0; m < 4; ++m) _Pragma("unroll") for (int n = 0; n < 2; ++n) _Pragma("unroll") for (int k = 0; k < 2; ++k) \
;         acc[ai][bj][m][n] = __builtin_amdgcn_mfma_f32_16x16x32_bf16(Bt[n][k], At[m][k], acc[ai][bj][m][n], 0, 0, 0); __builtin_amdgcn_s_setprio(0); } while (0)
; #define PG8_WAIT_V(n) asm volatile("s_waitcnt vmcnt(" #n ")" ::: "memory")
; #define PG8_WAIT_L(n) asm volatile("s_waitcnt lgkmcnt(" #n ")" ::: "memory")
; #define PG8_BAR __builtin_amdgcn_s_barrier()
; #define PG8_SCHED __builtin_amdgcn_sched_barrier(0)
; template <class Epi, class Sched, bool ALIGN_EPI, bool SP2, bool PERMA = false>
; __device__ __forceinline__ void gemm_phase(LAS unsigned char* lds, const int tid, const int lda, const int ldb, const Sched& S, const Epi& E) {
;     ...
;             PG8_WAIT_V(8); PG8_WAIT_L(0); PG8_BAR; PG8_MMA(1, 0, At, B0); PG8_MMA(1, 1, At, B1); PG8_BAR; PG8_SCHED;
;             PG8_LDB(B0, 1, 0); PG8_LDB(B1, 1, 1); PG8_SCHED; PG8_LDA(At, 1, 0); PG8_STAGE(PG8_SA(0, 1), a2 + hsA, voffA);
;             PG8_WAIT_V(8); PG8_WAIT_L(0); PG8_BAR; PG8_MMA(0, 0, At, B0); PG8_MMA(0, 1, At, B1); PG8_BAR; PG8_SCHED;
	s_setprio 1
	s_waitcnt lgkmcnt(0)
	v_mfma_f32_16x16x32_bf16 v[60:63], v[128:131], v[166:169], 0
	v_mfma_f32_16x16x32_bf16 v[56:59], v[136:139], v[166:169], 0
	v_mfma_f32_16x16x32_bf16 v[52:55], v[128:131], v[174:177], 0
	v_mfma_f32_16x16x32_bf16 v[44:47], v[136:139], v[174:177], 0
	v_mfma_f32_16x16x32_bf16 v[36:39], v[128:131], v[182:185], 0
	v_mfma_f32_16x16x32_bf16 v[28:31], v[136:139], v[182:185], 0
	v_mfma_f32_16x16x32_bf16 v[20:23], v[128:131], v[200:203], 0
	v_mfma_f32_16x16x32_bf16 v[12:15], v[136:139], v[200:203], 0
	v_mfma_f32_16x16x32_bf16 v[60:63], v[132:135], v[170:173], v[60:63]
	v_mfma_f32_16x16x32_bf16 v[56:59], v[140:143], v[170:173], v[56:59]
	v_mfma_f32_16x16x32_bf16 v[52:55], v[132:135], v[178:181], v[52:55]
	v_mfma_f32_16x16x32_bf16 v[44:47], v[140:143], v[178:181], v[44:47]
	v_mfma_f32_16x16x32_bf16 v[36:39], v[132:135], v[186:189], v[36:39]
	v_mfma_f32_16x16x32_bf16 v[28:31], v[140:143], v[186:189], v[28:31]
	v_mfma_f32_16x16x32_bf16 v[20:23], v[132:135], v[204:207], v[20:23]
	v_mfma_f32_16x16x32_bf16 v[12:15], v[140:143], v[204:207], v[12:15]
	s_setprio 0
	s_setprio 1
	v_mfma_f32_16x16x32_bf16 v[48:51], v[144:147], v[166:169], 0
	v_mfma_f32_16x16x32_bf16 v[40:43], v[152:155], v[166:169], 0
	v_mfma_f32_16x16x32_bf16 v[32:35], v[144:147], v[174:177], 0
	v_mfma_f32_16x16x32_bf16 v[24:27], v[152:155], v[174:177], 0
	v_mfma_f32_16x16x32_bf16 v[16:19], v[144:147], v[182:185], 0
	v_mfma_f32_16x16x32_bf16 v[8:11], v[152:155], v[182:185], 0
	v_mfma_f32_16x16x32_bf16 v[4:7], v[144:147], v[200:203], 0
	v_mfma_f32_16x16x32_bf16 v[0:3], v[152:155], v[200:203], 0
	v_mfma_f32_16x16x32_bf16 v[48:51], v[148:151], v[170:173], v[48:51]
	v_mfma_f32_16x16x32_bf16 v[40:43], v[156:159], v[170:173], v[40:43]
	v_mfma_f32_16x16x32_bf16 v[32:35], v[148:151], v[178:181], v[32:35]
	v_mfma_f32_16x16x32_bf16 v[24:27], v[156:159], v[178:181], v[24:27]
	v_mfma_f32_16x16x32_bf16 v[16:19], v[148:151], v[186:189], v[16:19]
	v_mfma_f32_16x16x32_bf16 v[8:11], v[156:159], v[186:189], v[8:11]
	v_mfma_f32_16x16x32_bf16 v[4:7], v[148:151], v[204:207], v[4:7]
	v_mfma_f32_16x16x32_bf16 v[0:3], v[156:159], v[204:207], v[0:3]
	s_setprio 0
	s_barrier
	s_add_i32 s60, 0, 0x18000
	s_add_i32 s61, 0, 0x1c000
	v_add_u32_e32 v140, s60, v197
	v_add_u32_e32 v156, s61, v197
	ds_read_b128 v[128:131], v140
	ds_read_b128 v[132:135], v140 offset:1024
	ds_read_b128 v[136:139], v140 offset:2048
	ds_read_b128 v[140:143], v140 offset:3072
	ds_read_b128 v[144:147], v156
	ds_read_b128 v[148:151], v156 offset:1024
	ds_read_b128 v[152:155], v156 offset:2048
	ds_read_b128 v[156:159], v156 offset:3072
	s_add_u32 s18, s26, 0xb0000
	s_addc_u32 s19, s27, 0
	s_mov_b32 m0, s29
	v_lshl_add_u64 v[216:217], s[18:19], 0, v[192:193]
	ds_read_b128 v[166:169], v198 offset:32768
	ds_read_b128 v[170:173], v198 offset:33792
	ds_read_b128 v[174:177], v198 offset:34816
	ds_read_b128 v[178:181], v198 offset:35840
	ds_read_b128 v[182:185], v198 offset:36864
	ds_read_b128 v[186:189], v198 offset:37888
	ds_read_b128 v[200:203], v198 offset:38912
	ds_read_b128 v[204:207], v198 offset:39936
	global_load_lds_dwordx4 v[216:217], off
	v_lshl_add_u64 v[216:217], s[18:19], 0, v[160:161]
	s_mov_b32 m0, s30
	s_nop 0
	global_load_lds_dwordx4 v[216:217], off
	s_waitcnt vmcnt(8)
	s_waitcnt lgkmcnt(0)
	s_barrier
	s_setprio 1
	s_waitcnt lgkmcnt(0)
	v_mfma_f32_16x16x32_bf16 v[124:127], v[128:131], v[166:169], v[124:127]
	v_mfma_f32_16x16x32_bf16 v[120:123], v[136:139], v[166:169], v[120:123]
	v_mfma_f32_16x16x32_bf16 v[116:119], v[128:131], v[174:177], v[116:119]
	v_mfma_f32_16x16x32_bf16 v[108:111], v[136:139], v[174:177], v[108:111]
	v_mfma_f32_16x16x32_bf16 v[100:103], v[128:131], v[182:185], v[100:103]
	v_mfma_f32_16x16x32_bf16 v[92:95], v[136:139], v[182:185], v[92:95]
	v_mfma_f32_16x16x32_bf16 v[84:87], v[128:131], v[200:203], v[84:87]
	v_mfma_f32_16x16x32_bf16 v[76:79], v[136:139], v[200:203], v[76:79]
	v_mfma_f32_16x16x32_bf16 v[124:127], v[132:135], v[170:173], v[124:127]
	v_mfma_f32_16x16x32_bf16 v[120:123], v[140:143], v[170:173], v[120:123]
	v_mfma_f32_16x16x32_bf16 v[116:119], v[132:135], v[178:181], v[116:119]
	v_mfma_f32_16x16x32_bf16 v[108:111], v[140:143], v[178:181], v[108:111]
	v_mfma_f32_16x16x32_bf16 v[100:103], v[132:135], v[186:189], v[100:103]
	v_mfma_f32_16x16x32_bf16 v[92:95], v[140:143], v[186:189], v[92:95]
	v_mfma_f32_16x16x32_bf16 v[84:87], v[132:135], v[204:207], v[84:87]
	v_mfma_f32_16x16x32_bf16 v[76:79], v[140:143], v[204:207], v[76:79]
	s_setprio 0
	s_setprio 1
	v_mfma_f32_16x16x32_bf16 v[112:115], v[144:147], v[166:169], v[112:115]
	v_mfma_f32_16x16x32_bf16 v[104:107], v[152:155], v[166:169], v[104:107]
	v_mfma_f32_16x16x32_bf16 v[96:99], v[144:147], v[174:177], v[96:99]
	v_mfma_f32_16x16x32_bf16 v[88:91], v[152:155], v[174:177], v[88:91]
	v_mfma_f32_16x16x32_bf16 v[80:83], v[144:147], v[182:185], v[80:83]
	v_mfma_f32_16x16x32_bf16 v[72:75], v[152:155], v[182:185], v[72:75]
	v_mfma_f32_16x16x32_bf16 v[68:71], v[144:147], v[200:203], v[68:71]
	v_mfma_f32_16x16x32_bf16 v[64:67], v[152:155], v[200:203], v[64:67]
	v_mfma_f32_16x16x32_bf16 v[112:115], v[148:151], v[170:173], v[112:115]
	v_mfma_f32_16x16x32_bf16 v[104:107], v[156:159], v[170:173], v[104:107]
	v_mfma_f32_16x16x32_bf16 v[96:99], v[148:151], v[178:181], v[96:99]
	v_mfma_f32_16x16x32_bf16 v[88:91], v[156:159], v[178:181], v[88:91]
	v_mfma_f32_16x16x32_bf16 v[80:83], v[148:151], v[186:189], v[80:83]
	v_mfma_f32_16x16x32_bf16 v[72:75], v[156:159], v[186:189], v[72:75]
	v_mfma_f32_16x16x32_bf16 v[68:71], v[148:151], v[204:207], v[68:71]
	v_mfma_f32_16x16x32_bf16 v[64:67], v[156:159], v[204:207], v[64:67]
	s_setprio 0
	s_barrier
; #define PG8_STAGE(bufoff, gbase, voff) do { _Pragma("unroll") for (int _i = 0; _i < 2; ++_i) \
;         __builtin_amdgcn_global_load_lds((const unsigned*)((const char*)(gbase) + (voff)[_i]), (LAS unsigned*)(lds + (bufoff) + ldsw + _i * 8192), 16, 0, 0); } while (0)
; #define PG8_LDA(dst, b, h) do { _Pragma("unroll") for (int m = 0; m < 4; ++m) _Pragma("unroll") for (int k = 0; k < 2; ++k) dst[m][k] = *(const LAS bf16x8*)(lds + PG8_SA(b, h) + aoff + m * 2048 + k * 1024); } while (0)
; #define PG8_LDB(dst, b, h) do { _Pragma("unroll") for (int n = 0; n < 2; ++n) _Pragma("unroll") for (int k = 0; k < 2; ++k) dst[n][k] = *(const LAS bf16x8*)(lds + PG8_SB(b, h) + boff + n * 2048 + k * 1024); } while (0)
; #define PG8_BAR __builtin_amdgcn_s_barrier()
; template <class Epi, class Sched, bool ALIGN_EPI, bool SP2, bool PERMA = false>
; __device__ __forceinline__ void gemm_phase(LAS unsigned char* lds, const int tid, const int lda, const int ldb, const Sched& S, const Epi& E) {
;     ...
;         for (int t = 0; t < nt; t += 2) {
;             const bool last = (t == nt - 2);
;             const char* a1 = cA + (size_t)(t + 1) * kstep;
;             const char* a2 = last ? nA : cA + (size_t)(t + 2) * kstep; const char* b2 = last ? nB : cB + (size_t)(t + 2) * kstep;
;             const char* a3 = a2 + kstep; const char* b3 = b2 + kstep;
;             if constexpr (SP2) {
;             PG8_LDB(B0, 0, 0); PG8_LDB(B1, 0, 1); PG8_SCHED; PG8_LDA(At, 0, 0); PG8_STAGE(PG8_SA(1, 1), a1 + hsA, voffA);
;             PG8_WAIT_V(8); PG8_WAIT_L(0); PG8_BAR; PG8_MMA(0, 0, At, B0); PG8_MMA(0, 1, At, B1); PG8_BAR; PG8_SCHED;
;             PG8_LDA(At, 0, 1); PG8_STAGE(PG8_SB(0, 0), b2, voffB); PG8_STAGE(PG8_SB(0, 1), b2 + hsB, voffB); PG8_STAGE(PG8_SA(0, 0), a2, voffA);
;             PG8_WAIT_V(8); PG8_WAIT_L(0); PG8_BAR; PG8_MMA(1, 0, At, B0); PG8_MMA(1, 1, At, B1); PG8_BAR; PG8_SCHED;
;             PG8_LDB(B0, 1, 0); PG8_LDB(B1, 1, 1); PG8_SCHED; PG8_LDA(At, 1, 0); PG8_STAGE(PG8_SA(0, 1), a2 + hsA, voffA);
;             PG8_WAIT_V(8); PG8_WAIT_L(0); PG8_BAR; PG8_MMA(0, 0, At, B0); PG8_MMA(0, 1, At, B1); PG8_BAR; PG8_SCHED;
;             PG8_LDA(At, 1, 1); PG8_STAGE(PG8_SB(1, 0), b3, voffB); PG8_STAGE(PG8_SB(1, 1), b3 + hsB, voffB); PG8_STAGE(PG8_SA(1, 0), a3, voffA);
;             PG8_WAIT_V(8); PG8_WAIT_L(0); PG8_BAR; PG8_MMA(1, 0, At, B0); PG8_MMA(1, 1, At, B1); PG8_BAR; PG8_SCHED;
	s_add_i32 s18, s60, s22
	v_lshl_add_u64 v[208:209], v[208:209], 0, s[54:55]
	s_mov_b32 m0, s18
	ds_read_b128 v[166:169], v198 offset:49152
	ds_read_b128 v[170:173], v198 offset:50176
	ds_read_b128 v[174:177], v198 offset:51200
	ds_read_b128 v[178:181], v198 offset:52224
	ds_read_b128 v[182:185], v198 offset:53248
	ds_read_b128 v[186:189], v198 offset:54272
	ds_read_b128 v[200:203], v198 offset:55296
	ds_read_b128 v[204:207], v198 offset:56320
	global_load_lds_dwordx4 v[208:209], off
	s_add_i32 m0, s18, 0x2000
	s_add_u32 s18, s24, 0xb0080
	v_lshl_add_u64 v[208:209], v[210:211], 0, s[54:55]
	s_addc_u32 s19, s25, 0
	s_add_i32 s24, s61, s22
	global_load_lds_dwordx4 v[208:209], off
	v_lshl_add_u64 v[208:209], s[18:19], 0, v[192:193]
	s_mov_b32 m0, s24
	s_nop 0
	global_load_lds_dwordx4 v[208:209], off
	v_lshl_add_u64 v[208:209], s[18:19], 0, v[160:161]
	s_add_i32 m0, s24, 0x2000
	s_nop 0
	global_load_lds_dwordx4 v[208:209], off
	v_lshl_add_u64 v[208:209], v[212:213], 0, s[54:55]
	s_mov_b32 m0, s49
	s_nop 0
	global_load_lds_dwordx4 v[208:209], off
	v_lshl_add_u64 v[208:209], v[214:215], 0, s[54:55]
	s_mov_b32 m0, s50
	s_nop 0
	global_load_lds_dwordx4 v[208:209], off
	s_waitcnt vmcnt(8)
	s_waitcnt lgkmcnt(0)
	s_barrier
	s_setprio 1
	s_waitcnt lgkmcnt(0)
	v_mfma_f32_16x16x32_bf16 v[60:63], v[128:131], v[166:169], v[60:63]
	v_mfma_f32_16x16x32_bf16 v[56:59], v[136:139], v[166:169], v[56:59]
	v_mfma_f32_16x16x32_bf16 v[52:55], v[128:131], v[174:177], v[52:55]
	v_mfma_f32_16x16x32_bf16 v[44:47], v[136:139], v[174:177], v[44:47]
	v_mfma_f32_16x16x32_bf16 v[36:39], v[128:131], v[182:185], v[36:39]
	v_mfma_f32_16x16x32_bf16 v[28:31], v[136:139], v[182:185], v[28:31]
	v_mfma_f32_16x16x32_bf16 v[20:23], v[128:131], v[200:203], v[20:23]
	v_mfma_f32_16x16x32_bf16 v[12:15], v[136:139], v[200:203], v[12:15]
	v_mfma_f32_16x16x32_bf16 v[60:63], v[132:135], v[170:173], v[60:63]
	v_mfma_f32_16x16x32_bf16 v[56:59], v[140:143], v[170:173], v[56:59]
	v_mfma_f32_16x16x32_bf16 v[52:55], v[132:135], v[178:181], v[52:55]
	v_mfma_f32_16x16x32_bf16 v[44:47], v[140:143], v[178:181], v[44:47]
	v_mfma_f32_16x16x32_bf16 v[36:39], v[132:135], v[186:189], v[36:39]
	v_mfma_f32_16x16x32_bf16 v[28:31], v[140:143], v[186:189], v[28:31]
	v_mfma_f32_16x16x32_bf16 v[20:23], v[132:135], v[204:207], v[20:23]
	v_mfma_f32_16x16x32_bf16 v[12:15], v[140:143], v[204:207], v[12:15]
	s_setprio 0
	s_setprio 1
	v_mfma_f32_16x16x32_bf16 v[48:51], v[144:147], v[166:169], v[48:51]
	v_mfma_f32_16x16x32_bf16 v[40:43], v[152:155], v[166:169], v[40:43]
	v_mfma_f32_16x16x32_bf16 v[32:35], v[144:147], v[174:177], v[32:35]
	v_mfma_f32_16x16x32_bf16 v[24:27], v[152:155], v[174:177], v[24:27]
	v_mfma_f32_16x16x32_bf16 v[16:19], v[144:147], v[182:185], v[16:19]
	v_mfma_f32_16x16x32_bf16 v[8:11], v[152:155], v[182:185], v[8:11]
	v_mfma_f32_16x16x32_bf16 v[4:7], v[144:147], v[200:203], v[4:7]
	v_mfma_f32_16x16x32_bf16 v[0:3], v[152:155], v[200:203], v[0:3]
	v_mfma_f32_16x16x32_bf16 v[48:51], v[148:151], v[170:173], v[48:51]
	v_mfma_f32_16x16x32_bf16 v[40:43], v[156:159], v[170:173], v[40:43]
	v_mfma_f32_16x16x32_bf16 v[32:35], v[148:151], v[178:181], v[32:35]
	v_mfma_f32_16x16x32_bf16 v[24:27], v[156:159], v[178:181], v[24:27]
	v_mfma_f32_16x16x32_bf16 v[16:19], v[148:151], v[186:189], v[16:19]
	v_mfma_f32_16x16x32_bf16 v[8:11], v[156:159], v[186:189], v[8:11]
	v_mfma_f32_16x16x32_bf16 v[4:7], v[148:151], v[204:207], v[4:7]
	v_mfma_f32_16x16x32_bf16 v[0:3], v[156:159], v[204:207], v[0:3]
	s_setprio 0
	s_barrier
	s_add_u32 s2, s2, 0x100
	s_addc_u32 s3, s3, 0
	s_cmp_ge_i32 s35, s17
	s_mov_b64 s[18:19], s[20:21]
	s_mov_b32 s24, s35
	s_cbranch_scc1 .Lgemm0_kdone

; #define PG8_BAR __builtin_amdgcn_s_barrier()
; template <class Epi, class Sched, bool ALIGN_EPI, bool SP2, bool PERMA = false>
; __device__ __forceinline__ void gemm_phase(LAS unsigned char* lds, const int tid, const int lda, const int ldb, const Sched& S, const Epi& E) {
;     ...
;         }
;         if constexpr (ALIGN_EPI) { if (wr == 0) PG8_BAR; }
;         { int frl = fr, fql = fq; asm volatile("" : "+v"(frl), "+v"(fql)); E(acc, cur, wr, wc, frl, fql); }
.Lgemm0_kdone:
	v_readlane_b32 s2, v255, 1
	v_readlane_b32 s3, v255, 2
	s_and_b64 vcc, exec, s[2:3]
	s_cbranch_vccz .LBB0_67
	s_barrier

; #define PG8_STAGE(bufoff, gbase, voff) do { _Pragma("unroll") for (int _i = 0; _i < 2; ++_i) \
;         __builtin_amdgcn_global_load_lds((const unsigned*)((const char*)(gbase) + (voff)[_i]), (LAS unsigned*)(lds + (bufoff) + ldsw + _i * 8192), 16, 0, 0); } while (0)
; #define PG8_LDA(dst, b, h) do { _Pragma("unroll") for (int m = 0; m < 4; ++m) _Pragma("unroll") for (int k = 0; k < 2; ++k) dst[m][k] = *(const LAS bf16x8*)(lds + PG8_SA(b, h) + aoff + m * 2048 + k * 1024); } while (0)
; #define PG8_LDB(dst, b, h) do { _Pragma("unroll") for (int n = 0; n < 2; ++n) _Pragma("unroll") for (int k = 0; k < 2; ++k) dst[n][k] = *(const LAS bf16x8*)(lds + PG8_SB(b, h) + boff + n * 2048 + k * 1024); } while (0)
; #define PG8_WAIT_V(n) asm volatile("s_waitcnt vmcnt(" #n ")" ::: "memory")
; #define PG8_WAIT_L(n) asm volatile("s_waitcnt lgkmcnt(" #n ")" ::: "memory")
; #define PG8_BAR __builtin_amdgcn_s_barrier()
; #define PG8_SCHED __builtin_amdgcn_sched_barrier(0)
; template <class Epi, class Sched, bool ALIGN_EPI, bool SP2, bool PERMA = false>
; __device__ __forceinline__ void gemm_phase(LAS unsigned char* lds, const int tid, const int lda, const int ldb, const Sched& S, const Epi& E) {
;     ...
;     for (;;) {
;         const bool has_next = S.next(ui + 1, nxt);
;         const char* nA = has_next ? (const char*)nxt.A : cA; const char* nB = has_next ? (const char*)nxt.B : cB;
;         const int nt = cur.nt;
;         for (int t = 0; t < nt; t += 2) {
;             const bool last = (t == nt - 2);
;             const char* a1 = cA + (size_t)(t + 1) * kstep;
;             const char* a2 = last ? nA : cA + (size_t)(t + 2) * kstep; const char* b2 = last ? nB : cB + (size_t)(t + 2) * kstep;
;             const char* a3 = a2 + kstep; const char* b3 = b2 + kstep;
;             if constexpr (SP2) {
;             PG8_LDB(B0, 0, 0); PG8_LDB(B1, 0, 1); PG8_SCHED; PG8_LDA(At, 0, 0); PG8_STAGE(PG8_SA(1, 1), a1 + hsA, voffA);
;             PG8_WAIT_V(8); PG8_WAIT_L(0); PG8_BAR; PG8_MMA(0, 0, At, B0); PG8_MMA(0, 1, At, B1); PG8_BAR; PG8_SCHED;
;             PG8_LDA(At, 0, 1); PG8_STAGE(PG8_SB(0, 0), b2, voffB); PG8_STAGE(PG8_SB(0, 1), b2 + hsB, voffB); PG8_STAGE(PG8_SA(0, 0), a2, voffA);
;             PG8_WAIT_V(8); PG8_WAIT_L(0); PG8_BAR; PG8_MMA(1, 0, At, B0); PG8_MMA(1, 1, At, B1); PG8_BAR; PG8_SCHED;
.LBB0_114:
	s_and_b64 s[28:29], s[16:17], exec
	s_cselect_b32 s1, s15, s7
	s_cselect_b32 s3, s14, s6
	s_cselect_b32 s19, s21, s9
	s_cselect_b32 s25, s20, s8
	s_add_u32 s27, s8, 0x100
	v_mov_b32_e32 v0, 0
	s_addc_u32 s33, s9, 0
	s_mov_b32 s50, -2
	s_waitcnt vmcnt(0)
	s_waitcnt vmcnt(0)
	s_add_u32 s8, s6, 0x100
	s_addc_u32 s9, s7, 0
	s_add_i32 s60, 0, 0x10000
	s_cmp_eq_u32 s50, 12
	s_cselect_b32 s31, s1, s9
	s_cselect_b32 s30, s3, s8
	s_cselect_b32 s29, s19, s33
	s_cselect_b32 s28, s25, s27
	s_add_i32 s61, 0, 0x14000
	s_waitcnt lgkmcnt(0)
	v_add_u32_e32 v140, s60, v213
	v_add_u32_e32 v156, s61, v213
	ds_read_b128 v[128:131], v140
	ds_read_b128 v[132:135], v140 offset:1024
	ds_read_b128 v[136:139], v140 offset:2048
	ds_read_b128 v[140:143], v140 offset:3072
	ds_read_b128 v[144:147], v156
	ds_read_b128 v[148:151], v156 offset:1024
	ds_read_b128 v[152:155], v156 offset:2048
	ds_read_b128 v[156:159], v156 offset:3072
	v_lshl_add_u64 v[210:211], s[6:7], 0, v[170:171]
	s_add_i32 m0, s96, 0xc000
	ds_read_b128 v[172:175], v214
	ds_read_b128 v[176:179], v214 offset:1024
	ds_read_b128 v[180:183], v214 offset:2048
	ds_read_b128 v[184:187], v214 offset:3072
	ds_read_b128 v[188:191], v214 offset:4096
	ds_read_b128 v[198:201], v214 offset:5120
	ds_read_b128 v[202:205], v214 offset:6144
	ds_read_b128 v[206:209], v214 offset:7168
	global_load_lds_dwordx4 v[210:211], off
	v_lshl_add_u64 v[210:211], s[6:7], 0, v[168:169]
	s_add_i32 m0, s96, 0xe000
	s_nop 0
	global_load_lds_dwordx4 v[210:211], off
	s_waitcnt vmcnt(8)
	s_waitcnt lgkmcnt(0)
	s_barrier
	s_setprio 1
	s_waitcnt lgkmcnt(0)
	v_mfma_f32_16x16x32_bf16 v[124:127], v[128:131], v[172:175], 0
	v_mfma_f32_16x16x32_bf16 v[64:67], v[136:139], v[172:175], 0
	v_mfma_f32_16x16x32_bf16 v[116:119], v[128:131], v[180:183], 0
	v_mfma_f32_16x16x32_bf16 v[52:55], v[136:139], v[180:183], 0
	v_mfma_f32_16x16x32_bf16 v[112:115], v[128:131], v[188:191], 0
	v_mfma_f32_16x16x32_bf16 v[48:51], v[136:139], v[188:191], 0
	v_mfma_f32_16x16x32_bf16 v[108:111], v[128:131], v[202:205], 0
	v_mfma_f32_16x16x32_bf16 v[44:47], v[136:139], v[202:205], 0
	v_mfma_f32_16x16x32_bf16 v[124:127], v[132:135], v[176:179], v[124:127]
	v_mfma_f32_16x16x32_bf16 v[64:67], v[140:143], v[176:179], v[64:67]
	v_mfma_f32_16x16x32_bf16 v[116:119], v[132:135], v[184:187], v[116:119]
	v_mfma_f32_16x16x32_bf16 v[52:55], v[140:143], v[184:187], v[52:55]
	v_mfma_f32_16x16x32_bf16 v[112:115], v[132:135], v[198:201], v[112:115]
	v_mfma_f32_16x16x32_bf16 v[48:51], v[140:143], v[198:201], v[48:51]
	v_mfma_f32_16x16x32_bf16 v[108:111], v[132:135], v[206:209], v[108:111]
	v_mfma_f32_16x16x32_bf16 v[44:47], v[140:143], v[206:209], v[44:47]
	s_setprio 0
	s_setprio 1
	v_mfma_f32_16x16x32_bf16 v[120:123], v[144:147], v[172:175], 0
	v_mfma_f32_16x16x32_bf16 v[56:59], v[152:155], v[172:175], 0
	v_mfma_f32_16x16x32_bf16 v[104:107], v[144:147], v[180:183], 0
	v_mfma_f32_16x16x32_bf16 v[40:43], v[152:155], v[180:183], 0
	v_mfma_f32_16x16x32_bf16 v[100:103], v[144:147], v[188:191], 0
	v_mfma_f32_16x16x32_bf16 v[36:39], v[152:155], v[188:191], 0
	v_mfma_f32_16x16x32_bf16 v[96:99], v[144:147], v[202:205], 0
	v_mfma_f32_16x16x32_bf16 v[32:35], v[152:155], v[202:205], 0
	v_mfma_f32_16x16x32_bf16 v[120:123], v[148:151], v[176:179], v[120:123]
	v_mfma_f32_16x16x32_bf16 v[56:59], v[156:159], v[176:179], v[56:59]
	v_mfma_f32_16x16x32_bf16 v[104:107], v[148:151], v[184:187], v[104:107]
	v_mfma_f32_16x16x32_bf16 v[40:43], v[156:159], v[184:187], v[40:43]
	v_mfma_f32_16x16x32_bf16 v[100:103], v[148:151], v[198:201], v[100:103]
	v_mfma_f32_16x16x32_bf16 v[36:39], v[156:159], v[198:201], v[36:39]
	v_mfma_f32_16x16x32_bf16 v[96:99], v[148:151], v[206:209], v[96:99]
	v_mfma_f32_16x16x32_bf16 v[32:35], v[156:159], v[206:209], v[32:35]
	s_setprio 0
	s_barrier
	s_add_i32 s6, s60, s92
	v_lshl_add_u64 v[210:211], s[28:29], 0, v[162:163]
	s_mov_b32 m0, s6
	ds_read_b128 v[172:175], v214 offset:16384
	ds_read_b128 v[176:179], v214 offset:17408
	ds_read_b128 v[180:183], v214 offset:18432
	ds_read_b128 v[184:187], v214 offset:19456
	ds_read_b128 v[188:191], v214 offset:20480
	ds_read_b128 v[198:201], v214 offset:21504
	ds_read_b128 v[202:205], v214 offset:22528
	ds_read_b128 v[206:209], v214 offset:23552
	global_load_lds_dwordx4 v[210:211], off
	s_add_i32 m0, s6, 0x2000
	s_add_u32 s6, s28, 0x40000
	v_lshl_add_u64 v[216:217], s[28:29], 0, v[166:167]
	s_addc_u32 s7, s29, 0
	s_add_i32 s60, s61, s92
	global_load_lds_dwordx4 v[216:217], off
	v_lshl_add_u64 v[218:219], s[6:7], 0, v[162:163]
	s_mov_b32 m0, s60
	v_lshl_add_u64 v[220:221], s[30:31], 0, v[164:165]
	global_load_lds_dwordx4 v[218:219], off
	v_lshl_add_u64 v[218:219], s[6:7], 0, v[166:167]
	s_add_i32 m0, s60, 0x2000
	s_nop 0
	global_load_lds_dwordx4 v[218:219], off
	v_lshl_add_u64 v[218:219], s[30:31], 0, v[160:161]
	s_mov_b32 m0, s96
	s_nop 0
	global_load_lds_dwordx4 v[218:219], off
	s_mov_b32 m0, s22
	s_nop 0
	global_load_lds_dwordx4 v[220:221], off
	s_waitcnt vmcnt(8)
	s_waitcnt lgkmcnt(0)
	s_barrier
; #define PG8_STAGE(bufoff, gbase, voff) do { _Pragma("unroll") for (int _i = 0; _i < 2; ++_i) \
;         __builtin_amdgcn_global_load_lds((const unsigned*)((const char*)(gbase) + (voff)[_i]), (LAS unsigned*)(lds + (bufoff) + ldsw + _i * 8192), 16, 0, 0); } while (0)
; #define PG8_LDA(dst, b, h) do { _Pragma("unroll") for (int m = 0; m < 4; ++m) _Pragma("unroll") for (int k = 0; k < 2; ++k) dst[m][k] = *(const LAS bf16x8*)(lds + PG8_SA(b, h) + aoff + m * 2048 + k * 1024); } while (0)
; #define PG8_LDB(dst, b, h) do { _Pragma("unroll") for (int n = 0; n < 2; ++n) _Pragma("unroll") for (int k = 0; k < 2; ++k) dst[n][k] = *(const LAS bf16x8*)(lds + PG8_SB(b, h) + boff + n * 2048 + k * 1024); } while (0)
; #define PG8_MMA(ai, bj, At, Bt) do { __builtin_amdgcn_s_setprio(1); _Pragma("unroll") for (int m = 0; m < 4; ++m) _Pragma("unroll") for (int n = 0; n < 2; ++n) _Pragma("unroll") for (int k = 0; k < 2; ++k) \
;         acc[ai][bj][m][n] = __builtin_amdgcn_mfma_f32_16x16x32_bf16(Bt[n][k], At[m][k], acc[ai][bj][m][n], 0, 0, 0); __builtin_amdgcn_s_setprio(0); } while (0)
; #define PG8_WAIT_V(n) asm volatile("s_waitcnt vmcnt(" #n ")" ::: "memory")
; #define PG8_WAIT_L(n) asm volatile("s_waitcnt lgkmcnt(" #n ")" ::: "memory")
; #define PG8_BAR __builtin_amdgcn_s_barrier()
; #define PG8_SCHED __builtin_amdgcn_sched_barrier(0)
; template <class Epi, class Sched, bool ALIGN_EPI, bool SP2, bool PERMA = false>
; __device__ __forceinline__ void gemm_phase(LAS unsigned char* lds, const int tid, const int lda, const int ldb, const Sched& S, const Epi& E) {
;     ...
;             PG8_WAIT_V(8); PG8_WAIT_L(0); PG8_BAR; PG8_MMA(1, 0, At, B0); PG8_MMA(1, 1, At, B1); PG8_BAR; PG8_SCHED;
;             PG8_LDB(B0, 1, 0); PG8_LDB(B1, 1, 1); PG8_SCHED; PG8_LDA(At, 1, 0); PG8_STAGE(PG8_SA(0, 1), a2 + hsA, voffA);
;             PG8_WAIT_V(8); PG8_WAIT_L(0); PG8_BAR; PG8_MMA(0, 0, At, B0); PG8_MMA(0, 1, At, B1); PG8_BAR; PG8_SCHED;
	s_setprio 1
	s_waitcnt lgkmcnt(0)
	v_mfma_f32_16x16x32_bf16 v[92:95], v[128:131], v[172:175], 0
	v_mfma_f32_16x16x32_bf16 v[28:31], v[136:139], v[172:175], 0
	v_mfma_f32_16x16x32_bf16 v[84:87], v[128:131], v[180:183], 0
	v_mfma_f32_16x16x32_bf16 v[20:23], v[136:139], v[180:183], 0
	v_mfma_f32_16x16x32_bf16 v[80:83], v[128:131], v[188:191], 0
	v_mfma_f32_16x16x32_bf16 v[16:19], v[136:139], v[188:191], 0
	v_mfma_f32_16x16x32_bf16 v[76:79], v[128:131], v[202:205], 0
	v_mfma_f32_16x16x32_bf16 v[12:15], v[136:139], v[202:205], 0
	v_mfma_f32_16x16x32_bf16 v[92:95], v[132:135], v[176:179], v[92:95]
	v_mfma_f32_16x16x32_bf16 v[28:31], v[140:143], v[176:179], v[28:31]
	v_mfma_f32_16x16x32_bf16 v[84:87], v[132:135], v[184:187], v[84:87]
	v_mfma_f32_16x16x32_bf16 v[20:23], v[140:143], v[184:187], v[20:23]
	v_mfma_f32_16x16x32_bf16 v[80:83], v[132:135], v[198:201], v[80:83]
	v_mfma_f32_16x16x32_bf16 v[16:19], v[140:143], v[198:201], v[16:19]
	v_mfma_f32_16x16x32_bf16 v[76:79], v[132:135], v[206:209], v[76:79]
	v_mfma_f32_16x16x32_bf16 v[12:15], v[140:143], v[206:209], v[12:15]
	s_setprio 0
	s_setprio 1
	v_mfma_f32_16x16x32_bf16 v[88:91], v[144:147], v[172:175], 0
	v_mfma_f32_16x16x32_bf16 v[24:27], v[152:155], v[172:175], 0
	v_mfma_f32_16x16x32_bf16 v[72:75], v[144:147], v[180:183], 0
	v_mfma_f32_16x16x32_bf16 v[8:11], v[152:155], v[180:183], 0
	v_mfma_f32_16x16x32_bf16 v[68:71], v[144:147], v[188:191], 0
	v_mfma_f32_16x16x32_bf16 v[4:7], v[152:155], v[188:191], 0
	v_mfma_f32_16x16x32_bf16 v[60:63], v[144:147], v[202:205], 0
	v_mfma_f32_16x16x32_bf16 v[0:3], v[152:155], v[202:205], 0
	v_mfma_f32_16x16x32_bf16 v[88:91], v[148:151], v[176:179], v[88:91]
	v_mfma_f32_16x16x32_bf16 v[24:27], v[156:159], v[176:179], v[24:27]
	v_mfma_f32_16x16x32_bf16 v[72:75], v[148:151], v[184:187], v[72:75]
	v_mfma_f32_16x16x32_bf16 v[8:11], v[156:159], v[184:187], v[8:11]
	v_mfma_f32_16x16x32_bf16 v[68:71], v[148:151], v[198:201], v[68:71]
	v_mfma_f32_16x16x32_bf16 v[4:7], v[156:159], v[198:201], v[4:7]
	v_mfma_f32_16x16x32_bf16 v[60:63], v[148:151], v[206:209], v[60:63]
	v_mfma_f32_16x16x32_bf16 v[0:3], v[156:159], v[206:209], v[0:3]
	s_setprio 0
	s_barrier
	s_add_i32 s60, 0, 0x18000
	s_add_i32 s61, 0, 0x1c000
	v_add_u32_e32 v140, s60, v213
	v_add_u32_e32 v156, s61, v213
	ds_read_b128 v[128:131], v140
	ds_read_b128 v[132:135], v140 offset:1024
	ds_read_b128 v[136:139], v140 offset:2048
	ds_read_b128 v[140:143], v140 offset:3072
	ds_read_b128 v[144:147], v156
	ds_read_b128 v[148:151], v156 offset:1024
	ds_read_b128 v[152:155], v156 offset:2048
	ds_read_b128 v[156:159], v156 offset:3072
	s_add_u32 s6, s30, 0x2000
	s_addc_u32 s7, s31, 0
	s_mov_b32 m0, s23
	v_lshl_add_u64 v[222:223], s[6:7], 0, v[160:161]
	ds_read_b128 v[172:175], v214 offset:32768
	ds_read_b128 v[176:179], v214 offset:33792
	ds_read_b128 v[180:183], v214 offset:34816
	ds_read_b128 v[184:187], v214 offset:35840
	ds_read_b128 v[188:191], v214 offset:36864
	ds_read_b128 v[198:201], v214 offset:37888
	ds_read_b128 v[202:205], v214 offset:38912
	ds_read_b128 v[206:209], v214 offset:39936
	global_load_lds_dwordx4 v[222:223], off
	v_lshl_add_u64 v[222:223], s[6:7], 0, v[164:165]
	s_mov_b32 m0, s97
	s_nop 0
	global_load_lds_dwordx4 v[222:223], off
	s_waitcnt vmcnt(8)
	s_waitcnt lgkmcnt(0)
	s_barrier
	s_setprio 1
	s_waitcnt lgkmcnt(0)
	v_mfma_f32_16x16x32_bf16 v[124:127], v[128:131], v[172:175], v[124:127]
	v_mfma_f32_16x16x32_bf16 v[64:67], v[136:139], v[172:175], v[64:67]
	v_mfma_f32_16x16x32_bf16 v[116:119], v[128:131], v[180:183], v[116:119]
	v_mfma_f32_16x16x32_bf16 v[52:55], v[136:139], v[180:183], v[52:55]
	v_mfma_f32_16x16x32_bf16 v[112:115], v[128:131], v[188:191], v[112:115]
	v_mfma_f32_16x16x32_bf16 v[48:51], v[136:139], v[188:191], v[48:51]
	v_mfma_f32_16x16x32_bf16 v[108:111], v[128:131], v[202:205], v[108:111]
	v_mfma_f32_16x16x32_bf16 v[44:47], v[136:139], v[202:205], v[44:47]
	v_mfma_f32_16x16x32_bf16 v[124:127], v[132:135], v[176:179], v[124:127]
	v_mfma_f32_16x16x32_bf16 v[64:67], v[140:143], v[176:179], v[64:67]
	v_mfma_f32_16x16x32_bf16 v[116:119], v[132:135], v[184:187], v[116:119]
	v_mfma_f32_16x16x32_bf16 v[52:55], v[140:143], v[184:187], v[52:55]
	v_mfma_f32_16x16x32_bf16 v[112:115], v[132:135], v[198:201], v[112:115]
	v_mfma_f32_16x16x32_bf16 v[48:51], v[140:143], v[198:201], v[48:51]
	v_mfma_f32_16x16x32_bf16 v[108:111], v[132:135], v[206:209], v[108:111]
	v_mfma_f32_16x16x32_bf16 v[44:47], v[140:143], v[206:209], v[44:47]
	s_setprio 0
	s_setprio 1
	v_mfma_f32_16x16x32_bf16 v[120:123], v[144:147], v[172:175], v[120:123]
	v_mfma_f32_16x16x32_bf16 v[56:59], v[152:155], v[172:175], v[56:59]
	v_mfma_f32_16x16x32_bf16 v[104:107], v[144:147], v[180:183], v[104:107]
	v_mfma_f32_16x16x32_bf16 v[40:43], v[152:155], v[180:183], v[40:43]
	v_mfma_f32_16x16x32_bf16 v[100:103], v[144:147], v[188:191], v[100:103]
	v_mfma_f32_16x16x32_bf16 v[36:39], v[152:155], v[188:191], v[36:39]
	v_mfma_f32_16x16x32_bf16 v[96:99], v[144:147], v[202:205], v[96:99]
	v_mfma_f32_16x16x32_bf16 v[32:35], v[152:155], v[202:205], v[32:35]
	v_mfma_f32_16x16x32_bf16 v[120:123], v[148:151], v[176:179], v[120:123]
	v_mfma_f32_16x16x32_bf16 v[56:59], v[156:159], v[176:179], v[56:59]
	v_mfma_f32_16x16x32_bf16 v[104:107], v[148:151], v[184:187], v[104:107]
	v_mfma_f32_16x16x32_bf16 v[40:43], v[156:159], v[184:187], v[40:43]
	v_mfma_f32_16x16x32_bf16 v[100:103], v[148:151], v[198:201], v[100:103]
	v_mfma_f32_16x16x32_bf16 v[36:39], v[156:159], v[198:201], v[36:39]
	v_mfma_f32_16x16x32_bf16 v[96:99], v[148:151], v[206:209], v[96:99]
	v_mfma_f32_16x16x32_bf16 v[32:35], v[156:159], v[206:209], v[32:35]
	s_setprio 0
	s_barrier
; #define PG8_STAGE(bufoff, gbase, voff) do { _Pragma("unroll") for (int _i = 0; _i < 2; ++_i) \
;         __builtin_amdgcn_global_load_lds((const unsigned*)((const char*)(gbase) + (voff)[_i]), (LAS unsigned*)(lds + (bufoff) + ldsw + _i * 8192), 16, 0, 0); } while (0)
; #define PG8_LDA(dst, b, h) do { _Pragma("unroll") for (int m = 0; m < 4; ++m) _Pragma("unroll") for (int k = 0; k < 2; ++k) dst[m][k] = *(const LAS bf16x8*)(lds + PG8_SA(b, h) + aoff + m * 2048 + k * 1024); } while (0)
; #define PG8_LDB(dst, b, h) do { _Pragma("unroll") for (int n = 0; n < 2; ++n) _Pragma("unroll") for (int k = 0; k < 2; ++k) dst[n][k] = *(const LAS bf16x8*)(lds + PG8_SB(b, h) + boff + n * 2048 + k * 1024); } while (0)
; #define PG8_BAR __builtin_amdgcn_s_barrier()
; template <class Epi, class Sched, bool ALIGN_EPI, bool SP2, bool PERMA = false>
; __device__ __forceinline__ void gemm_phase(LAS unsigned char* lds, const int tid, const int lda, const int ldb, const Sched& S, const Epi& E) {
;     ...
;         for (int t = 0; t < nt; t += 2) {
;             const bool last = (t == nt - 2);
;             const char* a1 = cA + (size_t)(t + 1) * kstep;
;             const char* a2 = last ? nA : cA + (size_t)(t + 2) * kstep; const char* b2 = last ? nB : cB + (size_t)(t + 2) * kstep;
;             const char* a3 = a2 + kstep; const char* b3 = b2 + kstep;
;             if constexpr (SP2) {
;             PG8_LDB(B0, 0, 0); PG8_LDB(B1, 0, 1); PG8_SCHED; PG8_LDA(At, 0, 0); PG8_STAGE(PG8_SA(1, 1), a1 + hsA, voffA);
;             PG8_WAIT_V(8); PG8_WAIT_L(0); PG8_BAR; PG8_MMA(0, 0, At, B0); PG8_MMA(0, 1, At, B1); PG8_BAR; PG8_SCHED;
;             PG8_LDA(At, 0, 1); PG8_STAGE(PG8_SB(0, 0), b2, voffB); PG8_STAGE(PG8_SB(0, 1), b2 + hsB, voffB); PG8_STAGE(PG8_SA(0, 0), a2, voffA);
;             PG8_WAIT_V(8); PG8_WAIT_L(0); PG8_BAR; PG8_MMA(1, 0, At, B0); PG8_MMA(1, 1, At, B1); PG8_BAR; PG8_SCHED;
;             PG8_LDB(B0, 1, 0); PG8_LDB(B1, 1, 1); PG8_SCHED; PG8_LDA(At, 1, 0); PG8_STAGE(PG8_SA(0, 1), a2 + hsA, voffA);
;             PG8_WAIT_V(8); PG8_WAIT_L(0); PG8_BAR; PG8_MMA(0, 0, At, B0); PG8_MMA(0, 1, At, B1); PG8_BAR; PG8_SCHED;
;             PG8_LDA(At, 1, 1); PG8_STAGE(PG8_SB(1, 0), b3, voffB); PG8_STAGE(PG8_SB(1, 1), b3 + hsB, voffB); PG8_STAGE(PG8_SA(1, 0), a3, voffA);
;             PG8_WAIT_V(8); PG8_WAIT_L(0); PG8_BAR; PG8_MMA(1, 0, At, B0); PG8_MMA(1, 1, At, B1); PG8_BAR; PG8_SCHED;
	s_add_i32 s6, s60, s92
	v_lshl_add_u64 v[210:211], v[210:211], 0, s[54:55]
	s_mov_b32 m0, s6
	ds_read_b128 v[172:175], v214 offset:49152
	ds_read_b128 v[176:179], v214 offset:50176
	ds_read_b128 v[180:183], v214 offset:51200
	ds_read_b128 v[184:187], v214 offset:52224
	ds_read_b128 v[188:191], v214 offset:53248
	ds_read_b128 v[198:201], v214 offset:54272
	ds_read_b128 v[202:205], v214 offset:55296
	ds_read_b128 v[206:209], v214 offset:56320
	global_load_lds_dwordx4 v[210:211], off
	s_add_i32 m0, s6, 0x2000
	s_add_u32 s6, s28, 0x40080
	v_lshl_add_u64 v[210:211], v[216:217], 0, s[54:55]
	s_addc_u32 s7, s29, 0
	s_add_i32 s28, s61, s92
	global_load_lds_dwordx4 v[210:211], off
	v_lshl_add_u64 v[210:211], s[6:7], 0, v[162:163]
	s_mov_b32 m0, s28
	s_nop 0
	global_load_lds_dwordx4 v[210:211], off
	v_lshl_add_u64 v[210:211], s[6:7], 0, v[166:167]
	s_add_i32 m0, s28, 0x2000
	s_nop 0
	global_load_lds_dwordx4 v[210:211], off
	v_lshl_add_u64 v[210:211], v[218:219], 0, s[54:55]
	s_mov_b32 m0, s95
	s_nop 0
	global_load_lds_dwordx4 v[210:211], off
	v_lshl_add_u64 v[210:211], v[220:221], 0, s[54:55]
	s_mov_b32 m0, s34
	s_nop 0
	global_load_lds_dwordx4 v[210:211], off
	s_waitcnt vmcnt(8)
	s_waitcnt lgkmcnt(0)
	s_barrier
	s_setprio 1
	s_waitcnt lgkmcnt(0)
	v_mfma_f32_16x16x32_bf16 v[92:95], v[128:131], v[172:175], v[92:95]
	v_mfma_f32_16x16x32_bf16 v[28:31], v[136:139], v[172:175], v[28:31]
	v_mfma_f32_16x16x32_bf16 v[84:87], v[128:131], v[180:183], v[84:87]
	v_mfma_f32_16x16x32_bf16 v[20:23], v[136:139], v[180:183], v[20:23]
	v_mfma_f32_16x16x32_bf16 v[80:83], v[128:131], v[188:191], v[80:83]
	v_mfma_f32_16x16x32_bf16 v[16:19], v[136:139], v[188:191], v[16:19]
	v_mfma_f32_16x16x32_bf16 v[76:79], v[128:131], v[202:205], v[76:79]
	v_mfma_f32_16x16x32_bf16 v[12:15], v[136:139], v[202:205], v[12:15]
	v_mfma_f32_16x16x32_bf16 v[92:95], v[132:135], v[176:179], v[92:95]
	v_mfma_f32_16x16x32_bf16 v[28:31], v[140:143], v[176:179], v[28:31]
	v_mfma_f32_16x16x32_bf16 v[84:87], v[132:135], v[184:187], v[84:87]
	v_mfma_f32_16x16x32_bf16 v[20:23], v[140:143], v[184:187], v[20:23]
	v_mfma_f32_16x16x32_bf16 v[80:83], v[132:135], v[198:201], v[80:83]
	v_mfma_f32_16x16x32_bf16 v[16:19], v[140:143], v[198:201], v[16:19]
	v_mfma_f32_16x16x32_bf16 v[76:79], v[132:135], v[206:209], v[76:79]
	v_mfma_f32_16x16x32_bf16 v[12:15], v[140:143], v[206:209], v[12:15]
	s_setprio 0
	s_setprio 1
	v_mfma_f32_16x16x32_bf16 v[88:91], v[144:147], v[172:175], v[88:91]
	v_mfma_f32_16x16x32_bf16 v[24:27], v[152:155], v[172:175], v[24:27]
	v_mfma_f32_16x16x32_bf16 v[72:75], v[144:147], v[180:183], v[72:75]
	v_mfma_f32_16x16x32_bf16 v[8:11], v[152:155], v[180:183], v[8:11]
	v_mfma_f32_16x16x32_bf16 v[68:71], v[144:147], v[188:191], v[68:71]
	v_mfma_f32_16x16x32_bf16 v[4:7], v[152:155], v[188:191], v[4:7]
	v_mfma_f32_16x16x32_bf16 v[60:63], v[144:147], v[202:205], v[60:63]
	v_mfma_f32_16x16x32_bf16 v[0:3], v[152:155], v[202:205], v[0:3]
	v_mfma_f32_16x16x32_bf16 v[88:91], v[148:151], v[176:179], v[88:91]
	v_mfma_f32_16x16x32_bf16 v[24:27], v[156:159], v[176:179], v[24:27]
	v_mfma_f32_16x16x32_bf16 v[72:75], v[148:151], v[184:187], v[72:75]
	v_mfma_f32_16x16x32_bf16 v[8:11], v[156:159], v[184:187], v[8:11]
	v_mfma_f32_16x16x32_bf16 v[68:71], v[148:151], v[198:201], v[68:71]
	v_mfma_f32_16x16x32_bf16 v[4:7], v[156:159], v[198:201], v[4:7]
	v_mfma_f32_16x16x32_bf16 v[60:63], v[148:151], v[206:209], v[60:63]
	v_mfma_f32_16x16x32_bf16 v[0:3], v[156:159], v[206:209], v[0:3]
	s_setprio 0
	s_barrier
	s_add_i32 s50, s50, 2
	s_add_u32 s27, s27, 0x100
	s_addc_u32 s33, s33, 0
	s_cmp_gt_u32 s50, 13
	s_mov_b64 s[6:7], s[8:9]
	s_cbranch_scc1 .Lgemm1_kdone

; #define PG8_BAR __builtin_amdgcn_s_barrier()
; template <class Epi, class Sched, bool ALIGN_EPI, bool SP2, bool PERMA = false>
; __device__ __forceinline__ void gemm_phase(LAS unsigned char* lds, const int tid, const int lda, const int ldb, const Sched& S, const Epi& E) {
;     ...
;         if constexpr (ALIGN_EPI) { if (wr == 0) PG8_BAR; }
.Lgemm1_kdone:
	s_and_b64 vcc, exec, s[12:13]
	s_cbranch_vccz .LBB0_118
	s_barrier

; #define PG8_STAGE(bufoff, gbase, voff) do { _Pragma("unroll") for (int _i = 0; _i < 2; ++_i) \
;         __builtin_amdgcn_global_load_lds((const unsigned*)((const char*)(gbase) + (voff)[_i]), (LAS unsigned*)(lds + (bufoff) + ldsw + _i * 8192), 16, 0, 0); } while (0)
; #define PG8_LDA(dst, b, h) do { _Pragma("unroll") for (int m = 0; m < 4; ++m) _Pragma("unroll") for (int k = 0; k < 2; ++k) dst[m][k] = *(const LAS bf16x8*)(lds + PG8_SA(b, h) + aoff + m * 2048 + k * 1024); } while (0)
; #define PG8_LDB(dst, b, h) do { _Pragma("unroll") for (int n = 0; n < 2; ++n) _Pragma("unroll") for (int k = 0; k < 2; ++k) dst[n][k] = *(const LAS bf16x8*)(lds + PG8_SB(b, h) + boff + n * 2048 + k * 1024); } while (0)
; #define PG8_MMA(ai, bj, At, Bt) do { __builtin_amdgcn_s_setprio(1); _Pragma("unroll") for (int m = 0; m < 4; ++m) _Pragma("unroll") for (int n = 0; n < 2; ++n) _Pragma("unroll") for (int k = 0; k < 2; ++k) \
;         acc[ai][bj][m][n] = __builtin_amdgcn_mfma_f32_16x16x32_bf16(Bt[n][k], At[m][k], acc[ai][bj][m][n], 0, 0, 0); __builtin_amdgcn_s_setprio(0); } while (0)
; #define PG8_WAIT_V(n) asm volatile("s_waitcnt vmcnt(" #n ")" ::: "memory")
; #define PG8_WAIT_L(n) asm volatile("s_waitcnt lgkmcnt(" #n ")" ::: "memory")
; template <class Epi, class Sched, bool ALIGN_EPI, bool SP2, bool PERMA = false>
; __device__ __forceinline__ void gemm_phase(LAS unsigned char* lds, const int tid, const int lda, const int ldb, const Sched& S, const Epi& E) {
;     ...
;         const char* nA = has_next ? (const char*)nxt.A : cA; const char* nB = has_next ? (const char*)nxt.B : cB;
;         const int nt = cur.nt;
;         for (int t = 0; t < nt; t += 2) {
;             const bool last = (t == nt - 2);
;             const char* a1 = cA + (size_t)(t + 1) * kstep;
;             const char* a2 = last ? nA : cA + (size_t)(t + 2) * kstep; const char* b2 = last ? nB : cB + (size_t)(t + 2) * kstep;
;             const char* a3 = a2 + kstep; const char* b3 = b2 + kstep;
;             if constexpr (SP2) {
;             PG8_LDB(B0, 0, 0); PG8_LDB(B1, 0, 1); PG8_SCHED; PG8_LDA(At, 0, 0); PG8_STAGE(PG8_SA(1, 1), a1 + hsA, voffA);
;             PG8_WAIT_V(8); PG8_WAIT_L(0); PG8_BAR; PG8_MMA(0, 0, At, B0); PG8_MMA(0, 1, At, B1); PG8_BAR; PG8_SCHED;
;             PG8_LDA(At, 0, 1); PG8_STAGE(PG8_SB(0, 0), b2, voffB); PG8_STAGE(PG8_SB(0, 1), b2 + hsB, voffB); PG8_STAGE(PG8_SA(0, 0), a2, voffA);
.LBB0_197:
	s_and_b64 s[28:29], s[16:17], exec
	s_cselect_b32 s21, s31, s25
	s_cselect_b32 s33, s30, s24
	s_cselect_b32 s92, s7, s27
	s_cselect_b32 vcc_lo, s6, s26
	s_add_u32 vcc_hi, s26, 0x100
	s_addc_u32 s95, s27, 0
	s_add_u32 s24, s24, 0x40080
	v_mov_b32_e32 v0, 0
	s_addc_u32 s25, s25, 0
	s_mov_b32 s96, -2
	s_waitcnt vmcnt(0)
	s_add_u32 s26, s24, 0xfffc0080
	s_addc_u32 s27, s25, -1
	s_add_i32 s60, 0, 0x10000
	s_cmp_eq_u32 s96, 12
	s_cselect_b32 s29, s21, s27
	s_cselect_b32 s28, s33, s26
	s_cselect_b32 s27, s92, s95
	s_cselect_b32 s26, vcc_lo, vcc_hi
	s_add_i32 s64, 0, 0x14000
	s_waitcnt lgkmcnt(0)
	v_add_u32_e32 v140, s60, v199
	v_add_u32_e32 v156, s64, v199
	ds_read_b128 v[128:131], v140
	ds_read_b128 v[132:135], v140 offset:1024
	ds_read_b128 v[136:139], v140 offset:2048
	ds_read_b128 v[140:143], v140 offset:3072
	ds_read_b128 v[144:147], v156
	ds_read_b128 v[148:151], v156 offset:1024
	ds_read_b128 v[152:155], v156 offset:2048
	ds_read_b128 v[156:159], v156 offset:3072
	v_lshl_add_u64 v[190:191], s[24:25], 0, v[164:165]
	s_add_i32 m0, s34, 0xc000
	ds_read_b128 v[166:169], v200
	ds_read_b128 v[170:173], v200 offset:1024
	ds_read_b128 v[174:177], v200 offset:2048
	ds_read_b128 v[178:181], v200 offset:3072
	ds_read_b128 v[182:185], v200 offset:4096
	ds_read_b128 v[186:189], v200 offset:5120
	ds_read_b128 v[202:205], v200 offset:6144
	ds_read_b128 v[206:209], v200 offset:7168
	global_load_lds_dwordx4 v[190:191], off
	v_lshl_add_u64 v[190:191], s[24:25], 0, v[162:163]
	s_add_i32 m0, s34, 0xe000
	s_nop 0
	global_load_lds_dwordx4 v[190:191], off
	s_waitcnt vmcnt(8)
	s_waitcnt lgkmcnt(0)
	s_barrier
	s_setprio 1
	s_waitcnt lgkmcnt(0)
	v_mfma_f32_16x16x32_bf16 v[124:127], v[128:131], v[166:169], 0
	v_mfma_f32_16x16x32_bf16 v[120:123], v[136:139], v[166:169], 0
	v_mfma_f32_16x16x32_bf16 v[112:115], v[128:131], v[174:177], 0
	v_mfma_f32_16x16x32_bf16 v[108:111], v[136:139], v[174:177], 0
	v_mfma_f32_16x16x32_bf16 v[100:103], v[128:131], v[182:185], 0
	v_mfma_f32_16x16x32_bf16 v[92:95], v[136:139], v[182:185], 0
	v_mfma_f32_16x16x32_bf16 v[84:87], v[128:131], v[202:205], 0
	v_mfma_f32_16x16x32_bf16 v[76:79], v[136:139], v[202:205], 0
	v_mfma_f32_16x16x32_bf16 v[124:127], v[132:135], v[170:173], v[124:127]
	v_mfma_f32_16x16x32_bf16 v[120:123], v[140:143], v[170:173], v[120:123]
	v_mfma_f32_16x16x32_bf16 v[112:115], v[132:135], v[178:181], v[112:115]
	v_mfma_f32_16x16x32_bf16 v[108:111], v[140:143], v[178:181], v[108:111]
	v_mfma_f32_16x16x32_bf16 v[100:103], v[132:135], v[186:189], v[100:103]
	v_mfma_f32_16x16x32_bf16 v[92:95], v[140:143], v[186:189], v[92:95]
	v_mfma_f32_16x16x32_bf16 v[84:87], v[132:135], v[206:209], v[84:87]
	v_mfma_f32_16x16x32_bf16 v[76:79], v[140:143], v[206:209], v[76:79]
	s_setprio 0
	s_setprio 1
	v_mfma_f32_16x16x32_bf16 v[116:119], v[144:147], v[166:169], 0
	v_mfma_f32_16x16x32_bf16 v[104:107], v[152:155], v[166:169], 0
	v_mfma_f32_16x16x32_bf16 v[96:99], v[144:147], v[174:177], 0
	v_mfma_f32_16x16x32_bf16 v[88:91], v[152:155], v[174:177], 0
	v_mfma_f32_16x16x32_bf16 v[80:83], v[144:147], v[182:185], 0
	v_mfma_f32_16x16x32_bf16 v[72:75], v[152:155], v[182:185], 0
	v_mfma_f32_16x16x32_bf16 v[68:71], v[144:147], v[202:205], 0
	v_mfma_f32_16x16x32_bf16 v[64:67], v[152:155], v[202:205], 0
	v_mfma_f32_16x16x32_bf16 v[116:119], v[148:151], v[170:173], v[116:119]
	v_mfma_f32_16x16x32_bf16 v[104:107], v[156:159], v[170:173], v[104:107]
	v_mfma_f32_16x16x32_bf16 v[96:99], v[148:151], v[178:181], v[96:99]
	v_mfma_f32_16x16x32_bf16 v[88:91], v[156:159], v[178:181], v[88:91]
	v_mfma_f32_16x16x32_bf16 v[80:83], v[148:151], v[186:189], v[80:83]
	v_mfma_f32_16x16x32_bf16 v[72:75], v[156:159], v[186:189], v[72:75]
	v_mfma_f32_16x16x32_bf16 v[68:71], v[148:151], v[206:209], v[68:71]
	v_mfma_f32_16x16x32_bf16 v[64:67], v[156:159], v[206:209], v[64:67]
	s_setprio 0
	s_barrier
	s_add_i32 s60, s60, s19
	v_lshl_add_u64 v[190:191], s[26:27], 0, v[192:193]
	s_mov_b32 m0, s60
	ds_read_b128 v[166:169], v200 offset:16384
	ds_read_b128 v[170:173], v200 offset:17408
	ds_read_b128 v[174:177], v200 offset:18432
	ds_read_b128 v[178:181], v200 offset:19456
	ds_read_b128 v[182:185], v200 offset:20480
	ds_read_b128 v[186:189], v200 offset:21504
	ds_read_b128 v[202:205], v200 offset:22528
	ds_read_b128 v[206:209], v200 offset:23552
	global_load_lds_dwordx4 v[190:191], off
	s_add_i32 m0, s60, 0x2000
	s_add_u32 s60, s26, 0x40000
	v_lshl_add_u64 v[210:211], s[26:27], 0, v[160:161]
	s_addc_u32 s61, s27, 0
	s_add_i32 s64, s64, s19
	global_load_lds_dwordx4 v[210:211], off
	v_lshl_add_u64 v[212:213], s[60:61], 0, v[192:193]
	s_mov_b32 m0, s64
	v_lshl_add_u64 v[214:215], s[28:29], 0, v[160:161]
	global_load_lds_dwordx4 v[212:213], off
	v_lshl_add_u64 v[212:213], s[60:61], 0, v[160:161]
	s_add_i32 m0, s64, 0x2000
	s_nop 0
	global_load_lds_dwordx4 v[212:213], off
	v_lshl_add_u64 v[212:213], s[28:29], 0, v[192:193]
	s_mov_b32 m0, s34
	s_nop 0
	global_load_lds_dwordx4 v[212:213], off
	s_mov_b32 m0, s35
	s_nop 0
	global_load_lds_dwordx4 v[214:215], off
	s_waitcnt vmcnt(8)
	s_waitcnt lgkmcnt(0)
	s_barrier
; #define PG8_STAGE(bufoff, gbase, voff) do { _Pragma("unroll") for (int _i = 0; _i < 2; ++_i) \
;         __builtin_amdgcn_global_load_lds((const unsigned*)((const char*)(gbase) + (voff)[_i]), (LAS unsigned*)(lds + (bufoff) + ldsw + _i * 8192), 16, 0, 0); } while (0)
; #define PG8_LDA(dst, b, h) do { _Pragma("unroll") for (int m = 0; m < 4; ++m) _Pragma("unroll") for (int k = 0; k < 2; ++k) dst[m][k] = *(const LAS bf16x8*)(lds + PG8_SA(b, h) + aoff + m * 2048 + k * 1024); } while (0)
; #define PG8_LDB(dst, b, h) do { _Pragma("unroll") for (int n = 0; n < 2; ++n) _Pragma("unroll") for (int k = 0; k < 2; ++k) dst[n][k] = *(const LAS bf16x8*)(lds + PG8_SB(b, h) + boff + n * 2048 + k * 1024); } while (0)
; #define PG8_MMA(ai, bj, At, Bt) do { __builtin_amdgcn_s_setprio(1); _Pragma("unroll") for (int m = 0; m < 4; ++m) _Pragma("unroll") for (int n = 0; n < 2; ++n) _Pragma("unroll") for (int k = 0; k < 2; ++k) \
;         acc[ai][bj][m][n] = __builtin_amdgcn_mfma_f32_16x16x32_bf16(Bt[n][k], At[m][k], acc[ai][bj][m][n], 0, 0, 0); __builtin_amdgcn_s_setprio(0); } while (0)
; #define PG8_WAIT_V(n) asm volatile("s_waitcnt vmcnt(" #n ")" ::: "memory")
; #define PG8_WAIT_L(n) asm volatile("s_waitcnt lgkmcnt(" #n ")" ::: "memory")
; #define PG8_BAR __builtin_amdgcn_s_barrier()
; #define PG8_SCHED __builtin_amdgcn_sched_barrier(0)
; template <class Epi, class Sched, bool ALIGN_EPI, bool SP2, bool PERMA = false>
; __device__ __forceinline__ void gemm_phase(LAS unsigned char* lds, const int tid, const int lda, const int ldb, const Sched& S, const Epi& E) {
;     ...
;             PG8_WAIT_V(8); PG8_WAIT_L(0); PG8_BAR; PG8_MMA(1, 0, At, B0); PG8_MMA(1, 1, At, B1); PG8_BAR; PG8_SCHED;
;             PG8_LDB(B0, 1, 0); PG8_LDB(B1, 1, 1); PG8_SCHED; PG8_LDA(At, 1, 0); PG8_STAGE(PG8_SA(0, 1), a2 + hsA, voffA);
;             PG8_WAIT_V(8); PG8_WAIT_L(0); PG8_BAR; PG8_MMA(0, 0, At, B0); PG8_MMA(0, 1, At, B1); PG8_BAR; PG8_SCHED;
	s_setprio 1
	s_waitcnt lgkmcnt(0)
	v_mfma_f32_16x16x32_bf16 v[60:63], v[128:131], v[166:169], 0
	v_mfma_f32_16x16x32_bf16 v[56:59], v[136:139], v[166:169], 0
	v_mfma_f32_16x16x32_bf16 v[52:55], v[128:131], v[174:177], 0
	v_mfma_f32_16x16x32_bf16 v[44:47], v[136:139], v[174:177], 0
	v_mfma_f32_16x16x32_bf16 v[36:39], v[128:131], v[182:185], 0
	v_mfma_f32_16x16x32_bf16 v[28:31], v[136:139], v[182:185], 0
	v_mfma_f32_16x16x32_bf16 v[20:23], v[128:131], v[202:205], 0
	v_mfma_f32_16x16x32_bf16 v[12:15], v[136:139], v[202:205], 0
	v_mfma_f32_16x16x32_bf16 v[60:63], v[132:135], v[170:173], v[60:63]
	v_mfma_f32_16x16x32_bf16 v[56:59], v[140:143], v[170:173], v[56:59]
	v_mfma_f32_16x16x32_bf16 v[52:55], v[132:135], v[178:181], v[52:55]
	v_mfma_f32_16x16x32_bf16 v[44:47], v[140:143], v[178:181], v[44:47]
	v_mfma_f32_16x16x32_bf16 v[36:39], v[132:135], v[186:189], v[36:39]
	v_mfma_f32_16x16x32_bf16 v[28:31], v[140:143], v[186:189], v[28:31]
	v_mfma_f32_16x16x32_bf16 v[20:23], v[132:135], v[206:209], v[20:23]
	v_mfma_f32_16x16x32_bf16 v[12:15], v[140:143], v[206:209], v[12:15]
	s_setprio 0
	s_setprio 1
	v_mfma_f32_16x16x32_bf16 v[48:51], v[144:147], v[166:169], 0
	v_mfma_f32_16x16x32_bf16 v[40:43], v[152:155], v[166:169], 0
	v_mfma_f32_16x16x32_bf16 v[32:35], v[144:147], v[174:177], 0
	v_mfma_f32_16x16x32_bf16 v[24:27], v[152:155], v[174:177], 0
	v_mfma_f32_16x16x32_bf16 v[16:19], v[144:147], v[182:185], 0
	v_mfma_f32_16x16x32_bf16 v[8:11], v[152:155], v[182:185], 0
	v_mfma_f32_16x16x32_bf16 v[4:7], v[144:147], v[202:205], 0
	v_mfma_f32_16x16x32_bf16 v[0:3], v[152:155], v[202:205], 0
	v_mfma_f32_16x16x32_bf16 v[48:51], v[148:151], v[170:173], v[48:51]
	v_mfma_f32_16x16x32_bf16 v[40:43], v[156:159], v[170:173], v[40:43]
	v_mfma_f32_16x16x32_bf16 v[32:35], v[148:151], v[178:181], v[32:35]
	v_mfma_f32_16x16x32_bf16 v[24:27], v[156:159], v[178:181], v[24:27]
	v_mfma_f32_16x16x32_bf16 v[16:19], v[148:151], v[186:189], v[16:19]
	v_mfma_f32_16x16x32_bf16 v[8:11], v[156:159], v[186:189], v[8:11]
	v_mfma_f32_16x16x32_bf16 v[4:7], v[148:151], v[206:209], v[4:7]
	v_mfma_f32_16x16x32_bf16 v[0:3], v[156:159], v[206:209], v[0:3]
	s_setprio 0
	s_barrier
	s_add_i32 s60, 0, 0x18000
	s_add_i32 s61, 0, 0x1c000
	v_add_u32_e32 v140, s60, v199
	v_add_u32_e32 v156, s61, v199
	ds_read_b128 v[128:131], v140
	ds_read_b128 v[132:135], v140 offset:1024
	ds_read_b128 v[136:139], v140 offset:2048
	ds_read_b128 v[140:143], v140 offset:3072
	ds_read_b128 v[144:147], v156
	ds_read_b128 v[148:151], v156 offset:1024
	ds_read_b128 v[152:155], v156 offset:2048
	ds_read_b128 v[156:159], v156 offset:3072
	s_add_u32 s28, s28, 0x40000
	s_addc_u32 s29, s29, 0
	s_mov_b32 m0, s49
	v_lshl_add_u64 v[216:217], s[28:29], 0, v[192:193]
	ds_read_b128 v[166:169], v200 offset:32768
	ds_read_b128 v[170:173], v200 offset:33792
	ds_read_b128 v[174:177], v200 offset:34816
	ds_read_b128 v[178:181], v200 offset:35840
	ds_read_b128 v[182:185], v200 offset:36864
	ds_read_b128 v[186:189], v200 offset:37888
	ds_read_b128 v[202:205], v200 offset:38912
	ds_read_b128 v[206:209], v200 offset:39936
	global_load_lds_dwordx4 v[216:217], off
	v_lshl_add_u64 v[216:217], s[28:29], 0, v[160:161]
	s_mov_b32 m0, s50
	s_nop 0
	global_load_lds_dwordx4 v[216:217], off
	s_waitcnt vmcnt(8)
	s_waitcnt lgkmcnt(0)
	s_barrier
	s_setprio 1
	s_waitcnt lgkmcnt(0)
	v_mfma_f32_16x16x32_bf16 v[124:127], v[128:131], v[166:169], v[124:127]
	v_mfma_f32_16x16x32_bf16 v[120:123], v[136:139], v[166:169], v[120:123]
	v_mfma_f32_16x16x32_bf16 v[112:115], v[128:131], v[174:177], v[112:115]
	v_mfma_f32_16x16x32_bf16 v[108:111], v[136:139], v[174:177], v[108:111]
	v_mfma_f32_16x16x32_bf16 v[100:103], v[128:131], v[182:185], v[100:103]
	v_mfma_f32_16x16x32_bf16 v[92:95], v[136:139], v[182:185], v[92:95]
	v_mfma_f32_16x16x32_bf16 v[84:87], v[128:131], v[202:205], v[84:87]
	v_mfma_f32_16x16x32_bf16 v[76:79], v[136:139], v[202:205], v[76:79]
	v_mfma_f32_16x16x32_bf16 v[124:127], v[132:135], v[170:173], v[124:127]
	v_mfma_f32_16x16x32_bf16 v[120:123], v[140:143], v[170:173], v[120:123]
	v_mfma_f32_16x16x32_bf16 v[112:115], v[132:135], v[178:181], v[112:115]
	v_mfma_f32_16x16x32_bf16 v[108:111], v[140:143], v[178:181], v[108:111]
	v_mfma_f32_16x16x32_bf16 v[100:103], v[132:135], v[186:189], v[100:103]
	v_mfma_f32_16x16x32_bf16 v[92:95], v[140:143], v[186:189], v[92:95]
	v_mfma_f32_16x16x32_bf16 v[84:87], v[132:135], v[206:209], v[84:87]
	v_mfma_f32_16x16x32_bf16 v[76:79], v[140:143], v[206:209], v[76:79]
	s_setprio 0
	s_setprio 1
	v_mfma_f32_16x16x32_bf16 v[116:119], v[144:147], v[166:169], v[116:119]
	v_mfma_f32_16x16x32_bf16 v[104:107], v[152:155], v[166:169], v[104:107]
	v_mfma_f32_16x16x32_bf16 v[96:99], v[144:147], v[174:177], v[96:99]
	v_mfma_f32_16x16x32_bf16 v[88:91], v[152:155], v[174:177], v[88:91]
	v_mfma_f32_16x16x32_bf16 v[80:83], v[144:147], v[182:185], v[80:83]
	v_mfma_f32_16x16x32_bf16 v[72:75], v[152:155], v[182:185], v[72:75]
	v_mfma_f32_16x16x32_bf16 v[68:71], v[144:147], v[202:205], v[68:71]
	v_mfma_f32_16x16x32_bf16 v[64:67], v[152:155], v[202:205], v[64:67]
	v_mfma_f32_16x16x32_bf16 v[116:119], v[148:151], v[170:173], v[116:119]
	v_mfma_f32_16x16x32_bf16 v[104:107], v[156:159], v[170:173], v[104:107]
	v_mfma_f32_16x16x32_bf16 v[96:99], v[148:151], v[178:181], v[96:99]
	v_mfma_f32_16x16x32_bf16 v[88:91], v[156:159], v[178:181], v[88:91]
	v_mfma_f32_16x16x32_bf16 v[80:83], v[148:151], v[186:189], v[80:83]
	v_mfma_f32_16x16x32_bf16 v[72:75], v[156:159], v[186:189], v[72:75]
	v_mfma_f32_16x16x32_bf16 v[68:71], v[148:151], v[206:209], v[68:71]
	v_mfma_f32_16x16x32_bf16 v[64:67], v[156:159], v[206:209], v[64:67]
	s_setprio 0
	s_barrier
; #define PG8_STAGE(bufoff, gbase, voff) do { _Pragma("unroll") for (int _i = 0; _i < 2; ++_i) \
;         __builtin_amdgcn_global_load_lds((const unsigned*)((const char*)(gbase) + (voff)[_i]), (LAS unsigned*)(lds + (bufoff) + ldsw + _i * 8192), 16, 0, 0); } while (0)
; #define PG8_LDA(dst, b, h) do { _Pragma("unroll") for (int m = 0; m < 4; ++m) _Pragma("unroll") for (int k = 0; k < 2; ++k) dst[m][k] = *(const LAS bf16x8*)(lds + PG8_SA(b, h) + aoff + m * 2048 + k * 1024); } while (0)
; #define PG8_MMA(ai, bj, At, Bt) do { __builtin_amdgcn_s_setprio(1); _Pragma("unroll") for (int m = 0; m < 4; ++m) _Pragma("unroll") for (int n = 0; n < 2; ++n) _Pragma("unroll") for (int k = 0; k < 2; ++k) \
;         acc[ai][bj][m][n] = __builtin_amdgcn_mfma_f32_16x16x32_bf16(Bt[n][k], At[m][k], acc[ai][bj][m][n], 0, 0, 0); __builtin_amdgcn_s_setprio(0); } while (0)
; #define PG8_WAIT_V(n) asm volatile("s_waitcnt vmcnt(" #n ")" ::: "memory")
; #define PG8_WAIT_L(n) asm volatile("s_waitcnt lgkmcnt(" #n ")" ::: "memory")
; #define PG8_BAR __builtin_amdgcn_s_barrier()
; #define PG8_SCHED __builtin_amdgcn_sched_barrier(0)
; template <class Epi, class Sched, bool ALIGN_EPI, bool SP2, bool PERMA = false>
; __device__ __forceinline__ void gemm_phase(LAS unsigned char* lds, const int tid, const int lda, const int ldb, const Sched& S, const Epi& E) {
;     ...
;             PG8_LDA(At, 1, 1); PG8_STAGE(PG8_SB(1, 0), b3, voffB); PG8_STAGE(PG8_SB(1, 1), b3 + hsB, voffB); PG8_STAGE(PG8_SA(1, 0), a3, voffA);
;             PG8_WAIT_V(8); PG8_WAIT_L(0); PG8_BAR; PG8_MMA(1, 0, At, B0); PG8_MMA(1, 1, At, B1); PG8_BAR; PG8_SCHED;
	s_add_i32 s28, s60, s19
	v_lshl_add_u64 v[190:191], v[190:191], 0, s[54:55]
	s_mov_b32 m0, s28
	ds_read_b128 v[166:169], v200 offset:49152
	ds_read_b128 v[170:173], v200 offset:50176
	ds_read_b128 v[174:177], v200 offset:51200
	ds_read_b128 v[178:181], v200 offset:52224
	ds_read_b128 v[182:185], v200 offset:53248
	ds_read_b128 v[186:189], v200 offset:54272
	ds_read_b128 v[202:205], v200 offset:55296
	ds_read_b128 v[206:209], v200 offset:56320
	global_load_lds_dwordx4 v[190:191], off
	s_add_i32 m0, s28, 0x2000
	s_add_u32 s26, s26, 0x40080
	v_lshl_add_u64 v[190:191], v[210:211], 0, s[54:55]
	s_addc_u32 s27, s27, 0
	s_add_i32 s28, s61, s19
	global_load_lds_dwordx4 v[190:191], off
	v_lshl_add_u64 v[190:191], s[26:27], 0, v[192:193]
	s_mov_b32 m0, s28
	s_nop 0
	global_load_lds_dwordx4 v[190:191], off
	v_lshl_add_u64 v[190:191], s[26:27], 0, v[160:161]
	s_add_i32 m0, s28, 0x2000
	s_nop 0
	global_load_lds_dwordx4 v[190:191], off
	v_lshl_add_u64 v[190:191], v[212:213], 0, s[54:55]
	s_mov_b32 m0, s22
	s_nop 0
	global_load_lds_dwordx4 v[190:191], off
	v_lshl_add_u64 v[190:191], v[214:215], 0, s[54:55]
	s_mov_b32 m0, s23
	s_nop 0
	global_load_lds_dwordx4 v[190:191], off
	s_waitcnt vmcnt(8)
	s_waitcnt lgkmcnt(0)
	s_barrier
	s_setprio 1
	s_waitcnt lgkmcnt(0)
	v_mfma_f32_16x16x32_bf16 v[60:63], v[128:131], v[166:169], v[60:63]
	v_mfma_f32_16x16x32_bf16 v[56:59], v[136:139], v[166:169], v[56:59]
	v_mfma_f32_16x16x32_bf16 v[52:55], v[128:131], v[174:177], v[52:55]
	v_mfma_f32_16x16x32_bf16 v[44:47], v[136:139], v[174:177], v[44:47]
	v_mfma_f32_16x16x32_bf16 v[36:39], v[128:131], v[182:185], v[36:39]
	v_mfma_f32_16x16x32_bf16 v[28:31], v[136:139], v[182:185], v[28:31]
	v_mfma_f32_16x16x32_bf16 v[20:23], v[128:131], v[202:205], v[20:23]
	v_mfma_f32_16x16x32_bf16 v[12:15], v[136:139], v[202:205], v[12:15]
	v_mfma_f32_16x16x32_bf16 v[60:63], v[132:135], v[170:173], v[60:63]
	v_mfma_f32_16x16x32_bf16 v[56:59], v[140:143], v[170:173], v[56:59]
	v_mfma_f32_16x16x32_bf16 v[52:55], v[132:135], v[178:181], v[52:55]
	v_mfma_f32_16x16x32_bf16 v[44:47], v[140:143], v[178:181], v[44:47]
	v_mfma_f32_16x16x32_bf16 v[36:39], v[132:135], v[186:189], v[36:39]
	v_mfma_f32_16x16x32_bf16 v[28:31], v[140:143], v[186:189], v[28:31]
	v_mfma_f32_16x16x32_bf16 v[20:23], v[132:135], v[206:209], v[20:23]
	v_mfma_f32_16x16x32_bf16 v[12:15], v[140:143], v[206:209], v[12:15]
	s_setprio 0
	s_setprio 1
	v_mfma_f32_16x16x32_bf16 v[48:51], v[144:147], v[166:169], v[48:51]
	v_mfma_f32_16x16x32_bf16 v[40:43], v[152:155], v[166:169], v[40:43]
	v_mfma_f32_16x16x32_bf16 v[32:35], v[144:147], v[174:177], v[32:35]
	v_mfma_f32_16x16x32_bf16 v[24:27], v[152:155], v[174:177], v[24:27]
	v_mfma_f32_16x16x32_bf16 v[16:19], v[144:147], v[182:185], v[16:19]
	v_mfma_f32_16x16x32_bf16 v[8:11], v[152:155], v[182:185], v[8:11]
	v_mfma_f32_16x16x32_bf16 v[4:7], v[144:147], v[202:205], v[4:7]
	v_mfma_f32_16x16x32_bf16 v[0:3], v[152:155], v[202:205], v[0:3]
	v_mfma_f32_16x16x32_bf16 v[48:51], v[148:151], v[170:173], v[48:51]
	v_mfma_f32_16x16x32_bf16 v[40:43], v[156:159], v[170:173], v[40:43]
	v_mfma_f32_16x16x32_bf16 v[32:35], v[148:151], v[178:181], v[32:35]
	v_mfma_f32_16x16x32_bf16 v[24:27], v[156:159], v[178:181], v[24:27]
	v_mfma_f32_16x16x32_bf16 v[16:19], v[148:151], v[186:189], v[16:19]
	v_mfma_f32_16x16x32_bf16 v[8:11], v[156:159], v[186:189], v[8:11]
	v_mfma_f32_16x16x32_bf16 v[4:7], v[148:151], v[206:209], v[4:7]
	v_mfma_f32_16x16x32_bf16 v[0:3], v[156:159], v[206:209], v[0:3]
	s_setprio 0
	s_barrier
	s_add_i32 s96, s96, 2
	s_add_u32 vcc_hi, vcc_hi, 0x100
	s_addc_u32 s95, s95, 0
	s_add_u32 s24, s24, 0x100
	s_addc_u32 s25, s25, 0
	s_cmp_gt_u32 s96, 13
	s_cbranch_scc1 .Lgemm2_kdone

; #define PG8_BAR __builtin_amdgcn_s_barrier()
; template <class Epi, class Sched, bool ALIGN_EPI, bool SP2, bool PERMA = false>
; __device__ __forceinline__ void gemm_phase(LAS unsigned char* lds, const int tid, const int lda, const int ldb, const Sched& S, const Epi& E) {
;     ...
;         if constexpr (ALIGN_EPI) { if (wr == 0) PG8_BAR; }
.Lgemm2_kdone:
	v_readlane_b32 s8, v254, 63
	v_readlane_b32 s9, v255, 0
	s_and_b64 vcc, exec, s[8:9]
	s_cbranch_vccz .LBB0_201
	s_barrier

; #define PG8_STAGE(bufoff, gbase, voff) do { _Pragma("unroll") for (int _i = 0; _i < 2; ++_i) \
;         __builtin_amdgcn_global_load_lds((const unsigned*)((const char*)(gbase) + (voff)[_i]), (LAS unsigned*)(lds + (bufoff) + ldsw + _i * 8192), 16, 0, 0); } while (0)
; #define PG8_LDA(dst, b, h) do { _Pragma("unroll") for (int m = 0; m < 4; ++m) _Pragma("unroll") for (int k = 0; k < 2; ++k) dst[m][k] = *(const LAS bf16x8*)(lds + PG8_SA(b, h) + aoff + m * 2048 + k * 1024); } while (0)
; #define PG8_LDB(dst, b, h) do { _Pragma("unroll") for (int n = 0; n < 2; ++n) _Pragma("unroll") for (int k = 0; k < 2; ++k) dst[n][k] = *(const LAS bf16x8*)(lds + PG8_SB(b, h) + boff + n * 2048 + k * 1024); } while (0)
; #define PG8_MMA(ai, bj, At, Bt) do { __builtin_amdgcn_s_setprio(1); _Pragma("unroll") for (int m = 0; m < 4; ++m) _Pragma("unroll") for (int n = 0; n < 2; ++n) _Pragma("unroll") for (int k = 0; k < 2; ++k) \
;         acc[ai][bj][m][n] = __builtin_amdgcn_mfma_f32_16x16x32_bf16(Bt[n][k], At[m][k], acc[ai][bj][m][n], 0, 0, 0); __builtin_amdgcn_s_setprio(0); } while (0)
; #define PG8_WAIT_V(n) asm volatile("s_waitcnt vmcnt(" #n ")" ::: "memory")
; #define PG8_WAIT_L(n) asm volatile("s_waitcnt lgkmcnt(" #n ")" ::: "memory")
; template <class Epi, class Sched, bool ALIGN_EPI, bool SP2, bool PERMA = false>
; __device__ __forceinline__ void gemm_phase(LAS unsigned char* lds, const int tid, const int lda, const int ldb, const Sched& S, const Epi& E) {
;     ...
;         const char* nA = has_next ? (const char*)nxt.A : cA; const char* nB = has_next ? (const char*)nxt.B : cB;
;         const int nt = cur.nt;
;         for (int t = 0; t < nt; t += 2) {
;             const bool last = (t == nt - 2);
;             const char* a1 = cA + (size_t)(t + 1) * kstep;
;             const char* a2 = last ? nA : cA + (size_t)(t + 2) * kstep; const char* b2 = last ? nB : cB + (size_t)(t + 2) * kstep;
;             const char* a3 = a2 + kstep; const char* b3 = b2 + kstep;
;             if constexpr (SP2) {
;             PG8_LDB(B0, 0, 0); PG8_LDB(B1, 0, 1); PG8_SCHED; PG8_LDA(At, 0, 0); PG8_STAGE(PG8_SA(1, 1), a1 + hsA, voffA);
;             PG8_WAIT_V(8); PG8_WAIT_L(0); PG8_BAR; PG8_MMA(0, 0, At, B0); PG8_MMA(0, 1, At, B1); PG8_BAR; PG8_SCHED;
;             PG8_LDA(At, 0, 1); PG8_STAGE(PG8_SB(0, 0), b2, voffB); PG8_STAGE(PG8_SB(0, 1), b2 + hsB, voffB); PG8_STAGE(PG8_SA(0, 0), a2, voffA);
.LBB0_262:
	s_and_b64 s[10:11], s[18:19], exec
	s_cselect_b32 s14, s17, s9
	s_cselect_b32 s15, s16, s8
	s_cselect_b32 s33, s35, s1
	s_cselect_b32 s96, s34, s0
	s_add_i32 s97, s13, -2
	s_add_u32 vcc_lo, s0, 0x100
	s_addc_u32 vcc_hi, s1, 0
	s_add_u32 s0, s8, 0x40080
	v_mov_b32_e32 v0, 0
	s_addc_u32 s1, s9, 0
	s_mov_b32 s8, 0
	s_waitcnt vmcnt(0)
	s_add_i32 s21, s8, 2
	s_add_u32 s9, s0, 0xfffc0080
	s_addc_u32 s10, s1, -1
	s_add_i32 s60, 0, 0x10000
	s_cmp_eq_u32 s97, s8
	s_cselect_b32 s11, s14, s10
	s_cselect_b32 s10, s15, s9
	s_cselect_b32 s9, s33, vcc_hi
	s_cselect_b32 s8, s96, vcc_lo
	s_add_i32 s64, 0, 0x14000
	s_waitcnt lgkmcnt(0)
	v_add_u32_e32 v140, s60, v248
	v_add_u32_e32 v156, s64, v248
	ds_read_b128 v[128:131], v140
	ds_read_b128 v[132:135], v140 offset:1024
	ds_read_b128 v[136:139], v140 offset:2048
	ds_read_b128 v[140:143], v140 offset:3072
	ds_read_b128 v[144:147], v156
	ds_read_b128 v[148:151], v156 offset:1024
	ds_read_b128 v[152:155], v156 offset:2048
	ds_read_b128 v[156:159], v156 offset:3072
	v_lshl_add_u64 v[190:191], s[0:1], 0, v[176:177]
	s_add_i32 m0, s51, 0xc000
	ds_read_b128 v[160:163], v249
	ds_read_b128 v[164:167], v249 offset:1024
	ds_read_b128 v[178:181], v249 offset:2048
	ds_read_b128 v[182:185], v249 offset:3072
	ds_read_b128 v[186:189], v249 offset:4096
	ds_read_b128 v[198:201], v249 offset:5120
	ds_read_b128 v[202:205], v249 offset:6144
	ds_read_b128 v[206:209], v249 offset:7168
	global_load_lds_dwordx4 v[190:191], off
	v_lshl_add_u64 v[190:191], s[0:1], 0, v[174:175]
	s_add_i32 m0, s51, 0xe000
	s_nop 0
	global_load_lds_dwordx4 v[190:191], off
	s_waitcnt vmcnt(8)
	s_waitcnt lgkmcnt(0)
	s_barrier
	s_setprio 1
	s_waitcnt lgkmcnt(0)
	v_mfma_f32_16x16x32_bf16 v[124:127], v[128:131], v[160:163], 0
	v_mfma_f32_16x16x32_bf16 v[120:123], v[136:139], v[160:163], 0
	v_mfma_f32_16x16x32_bf16 v[108:111], v[128:131], v[178:181], 0
	v_mfma_f32_16x16x32_bf16 v[104:107], v[136:139], v[178:181], 0
	v_mfma_f32_16x16x32_bf16 v[92:95], v[128:131], v[186:189], 0
	v_mfma_f32_16x16x32_bf16 v[88:91], v[136:139], v[186:189], 0
	v_mfma_f32_16x16x32_bf16 v[76:79], v[128:131], v[202:205], 0
	v_mfma_f32_16x16x32_bf16 v[72:75], v[136:139], v[202:205], 0
	v_mfma_f32_16x16x32_bf16 v[124:127], v[132:135], v[164:167], v[124:127]
	v_mfma_f32_16x16x32_bf16 v[120:123], v[140:143], v[164:167], v[120:123]
	v_mfma_f32_16x16x32_bf16 v[108:111], v[132:135], v[182:185], v[108:111]
	v_mfma_f32_16x16x32_bf16 v[104:107], v[140:143], v[182:185], v[104:107]
	v_mfma_f32_16x16x32_bf16 v[92:95], v[132:135], v[198:201], v[92:95]
	v_mfma_f32_16x16x32_bf16 v[88:91], v[140:143], v[198:201], v[88:91]
	v_mfma_f32_16x16x32_bf16 v[76:79], v[132:135], v[206:209], v[76:79]
	v_mfma_f32_16x16x32_bf16 v[72:75], v[140:143], v[206:209], v[72:75]
	s_setprio 0
	s_setprio 1
	v_mfma_f32_16x16x32_bf16 v[116:119], v[144:147], v[160:163], 0
	v_mfma_f32_16x16x32_bf16 v[112:115], v[152:155], v[160:163], 0
	v_mfma_f32_16x16x32_bf16 v[100:103], v[144:147], v[178:181], 0
	v_mfma_f32_16x16x32_bf16 v[96:99], v[152:155], v[178:181], 0
	v_mfma_f32_16x16x32_bf16 v[84:87], v[144:147], v[186:189], 0
	v_mfma_f32_16x16x32_bf16 v[80:83], v[152:155], v[186:189], 0
	v_mfma_f32_16x16x32_bf16 v[68:71], v[144:147], v[202:205], 0
	v_mfma_f32_16x16x32_bf16 v[64:67], v[152:155], v[202:205], 0
	v_mfma_f32_16x16x32_bf16 v[116:119], v[148:151], v[164:167], v[116:119]
	v_mfma_f32_16x16x32_bf16 v[112:115], v[156:159], v[164:167], v[112:115]
	v_mfma_f32_16x16x32_bf16 v[100:103], v[148:151], v[182:185], v[100:103]
	v_mfma_f32_16x16x32_bf16 v[96:99], v[156:159], v[182:185], v[96:99]
	v_mfma_f32_16x16x32_bf16 v[84:87], v[148:151], v[198:201], v[84:87]
	v_mfma_f32_16x16x32_bf16 v[80:83], v[156:159], v[198:201], v[80:83]
	v_mfma_f32_16x16x32_bf16 v[68:71], v[148:151], v[206:209], v[68:71]
	v_mfma_f32_16x16x32_bf16 v[64:67], v[156:159], v[206:209], v[64:67]
	s_setprio 0
	s_barrier
	s_add_i32 s60, s60, s49
	v_lshl_add_u64 v[190:191], s[8:9], 0, v[192:193]
	s_mov_b32 m0, s60
	ds_read_b128 v[160:163], v249 offset:16384
	ds_read_b128 v[164:167], v249 offset:17408
	ds_read_b128 v[178:181], v249 offset:18432
	ds_read_b128 v[182:185], v249 offset:19456
	ds_read_b128 v[186:189], v249 offset:20480
	ds_read_b128 v[198:201], v249 offset:21504
	ds_read_b128 v[202:205], v249 offset:22528
	ds_read_b128 v[206:209], v249 offset:23552
	global_load_lds_dwordx4 v[190:191], off
	s_add_i32 m0, s60, 0x2000
	s_add_u32 s60, s8, 0x60000
	v_lshl_add_u64 v[210:211], s[8:9], 0, v[172:173]
	s_addc_u32 s61, s9, 0
	s_add_i32 s64, s64, s49
	global_load_lds_dwordx4 v[210:211], off
	v_lshl_add_u64 v[212:213], s[60:61], 0, v[192:193]
	s_mov_b32 m0, s64
	v_lshl_add_u64 v[214:215], s[10:11], 0, v[170:171]
	global_load_lds_dwordx4 v[212:213], off
	v_lshl_add_u64 v[212:213], s[60:61], 0, v[172:173]
	s_add_i32 m0, s64, 0x2000
	s_nop 0
	global_load_lds_dwordx4 v[212:213], off
	v_lshl_add_u64 v[212:213], s[10:11], 0, v[168:169]
	s_mov_b32 m0, s51
	s_nop 0
	global_load_lds_dwordx4 v[212:213], off
	s_mov_b32 m0, s30
	s_nop 0
	global_load_lds_dwordx4 v[214:215], off
	s_waitcnt vmcnt(8)
	s_waitcnt lgkmcnt(0)
	s_barrier
; #define PG8_STAGE(bufoff, gbase, voff) do { _Pragma("unroll") for (int _i = 0; _i < 2; ++_i) \
;         __builtin_amdgcn_global_load_lds((const unsigned*)((const char*)(gbase) + (voff)[_i]), (LAS unsigned*)(lds + (bufoff) + ldsw + _i * 8192), 16, 0, 0); } while (0)
; #define PG8_LDA(dst, b, h) do { _Pragma("unroll") for (int m = 0; m < 4; ++m) _Pragma("unroll") for (int k = 0; k < 2; ++k) dst[m][k] = *(const LAS bf16x8*)(lds + PG8_SA(b, h) + aoff + m * 2048 + k * 1024); } while (0)
; #define PG8_LDB(dst, b, h) do { _Pragma("unroll") for (int n = 0; n < 2; ++n) _Pragma("unroll") for (int k = 0; k < 2; ++k) dst[n][k] = *(const LAS bf16x8*)(lds + PG8_SB(b, h) + boff + n * 2048 + k * 1024); } while (0)
; #define PG8_MMA(ai, bj, At, Bt) do { __builtin_amdgcn_s_setprio(1); _Pragma("unroll") for (int m = 0; m < 4; ++m) _Pragma("unroll") for (int n = 0; n < 2; ++n) _Pragma("unroll") for (int k = 0; k < 2; ++k) \
;         acc[ai][bj][m][n] = __builtin_amdgcn_mfma_f32_16x16x32_bf16(Bt[n][k], At[m][k], acc[ai][bj][m][n], 0, 0, 0); __builtin_amdgcn_s_setprio(0); } while (0)
; #define PG8_WAIT_V(n) asm volatile("s_waitcnt vmcnt(" #n ")" ::: "memory")
; #define PG8_WAIT_L(n) asm volatile("s_waitcnt lgkmcnt(" #n ")" ::: "memory")
; #define PG8_BAR __builtin_amdgcn_s_barrier()
; #define PG8_SCHED __builtin_amdgcn_sched_barrier(0)
; template <class Epi, class Sched, bool ALIGN_EPI, bool SP2, bool PERMA = false>
; __device__ __forceinline__ void gemm_phase(LAS unsigned char* lds, const int tid, const int lda, const int ldb, const Sched& S, const Epi& E) {
;     ...
;             PG8_WAIT_V(8); PG8_WAIT_L(0); PG8_BAR; PG8_MMA(1, 0, At, B0); PG8_MMA(1, 1, At, B1); PG8_BAR; PG8_SCHED;
;             PG8_LDB(B0, 1, 0); PG8_LDB(B1, 1, 1); PG8_SCHED; PG8_LDA(At, 1, 0); PG8_STAGE(PG8_SA(0, 1), a2 + hsA, voffA);
;             PG8_WAIT_V(8); PG8_WAIT_L(0); PG8_BAR; PG8_MMA(0, 0, At, B0); PG8_MMA(0, 1, At, B1); PG8_BAR; PG8_SCHED;
	s_setprio 1
	s_waitcnt lgkmcnt(0)
	v_mfma_f32_16x16x32_bf16 v[60:63], v[128:131], v[160:163], 0
	v_mfma_f32_16x16x32_bf16 v[56:59], v[136:139], v[160:163], 0
	v_mfma_f32_16x16x32_bf16 v[44:47], v[128:131], v[178:181], 0
	v_mfma_f32_16x16x32_bf16 v[40:43], v[136:139], v[178:181], 0
	v_mfma_f32_16x16x32_bf16 v[28:31], v[128:131], v[186:189], 0
	v_mfma_f32_16x16x32_bf16 v[24:27], v[136:139], v[186:189], 0
	v_mfma_f32_16x16x32_bf16 v[12:15], v[128:131], v[202:205], 0
	v_mfma_f32_16x16x32_bf16 v[8:11], v[136:139], v[202:205], 0
	v_mfma_f32_16x16x32_bf16 v[60:63], v[132:135], v[164:167], v[60:63]
	v_mfma_f32_16x16x32_bf16 v[56:59], v[140:143], v[164:167], v[56:59]
	v_mfma_f32_16x16x32_bf16 v[44:47], v[132:135], v[182:185], v[44:47]
	v_mfma_f32_16x16x32_bf16 v[40:43], v[140:143], v[182:185], v[40:43]
	v_mfma_f32_16x16x32_bf16 v[28:31], v[132:135], v[198:201], v[28:31]
	v_mfma_f32_16x16x32_bf16 v[24:27], v[140:143], v[198:201], v[24:27]
	v_mfma_f32_16x16x32_bf16 v[12:15], v[132:135], v[206:209], v[12:15]
	v_mfma_f32_16x16x32_bf16 v[8:11], v[140:143], v[206:209], v[8:11]
	s_setprio 0
	s_setprio 1
	v_mfma_f32_16x16x32_bf16 v[52:55], v[144:147], v[160:163], 0
	v_mfma_f32_16x16x32_bf16 v[48:51], v[152:155], v[160:163], 0
	v_mfma_f32_16x16x32_bf16 v[36:39], v[144:147], v[178:181], 0
	v_mfma_f32_16x16x32_bf16 v[32:35], v[152:155], v[178:181], 0
	v_mfma_f32_16x16x32_bf16 v[20:23], v[144:147], v[186:189], 0
	v_mfma_f32_16x16x32_bf16 v[16:19], v[152:155], v[186:189], 0
	v_mfma_f32_16x16x32_bf16 v[4:7], v[144:147], v[202:205], 0
	v_mfma_f32_16x16x32_bf16 v[0:3], v[152:155], v[202:205], 0
	v_mfma_f32_16x16x32_bf16 v[52:55], v[148:151], v[164:167], v[52:55]
	v_mfma_f32_16x16x32_bf16 v[48:51], v[156:159], v[164:167], v[48:51]
	v_mfma_f32_16x16x32_bf16 v[36:39], v[148:151], v[182:185], v[36:39]
	v_mfma_f32_16x16x32_bf16 v[32:35], v[156:159], v[182:185], v[32:35]
	v_mfma_f32_16x16x32_bf16 v[20:23], v[148:151], v[198:201], v[20:23]
	v_mfma_f32_16x16x32_bf16 v[16:19], v[156:159], v[198:201], v[16:19]
	v_mfma_f32_16x16x32_bf16 v[4:7], v[148:151], v[206:209], v[4:7]
	v_mfma_f32_16x16x32_bf16 v[0:3], v[156:159], v[206:209], v[0:3]
	s_setprio 0
	s_barrier
	s_add_i32 s60, 0, 0x18000
	s_add_i32 s61, 0, 0x1c000
	v_add_u32_e32 v140, s60, v248
	v_add_u32_e32 v156, s61, v248
	ds_read_b128 v[128:131], v140
	ds_read_b128 v[132:135], v140 offset:1024
	ds_read_b128 v[136:139], v140 offset:2048
	ds_read_b128 v[140:143], v140 offset:3072
	ds_read_b128 v[144:147], v156
	ds_read_b128 v[148:151], v156 offset:1024
	ds_read_b128 v[152:155], v156 offset:2048
	ds_read_b128 v[156:159], v156 offset:3072
	s_add_u32 s10, s10, 0x40000
	s_addc_u32 s11, s11, 0
	s_mov_b32 m0, s31
	v_lshl_add_u64 v[216:217], s[10:11], 0, v[168:169]
	ds_read_b128 v[160:163], v249 offset:32768
	ds_read_b128 v[164:167], v249 offset:33792
	ds_read_b128 v[178:181], v249 offset:34816
	ds_read_b128 v[182:185], v249 offset:35840
	ds_read_b128 v[186:189], v249 offset:36864
	ds_read_b128 v[198:201], v249 offset:37888
	ds_read_b128 v[202:205], v249 offset:38912
	ds_read_b128 v[206:209], v249 offset:39936
	global_load_lds_dwordx4 v[216:217], off
	v_lshl_add_u64 v[216:217], s[10:11], 0, v[170:171]
	s_mov_b32 m0, s22
	s_nop 0
	global_load_lds_dwordx4 v[216:217], off
	s_waitcnt vmcnt(8)
	s_waitcnt lgkmcnt(0)
	s_barrier
	s_setprio 1
	s_waitcnt lgkmcnt(0)
	v_mfma_f32_16x16x32_bf16 v[124:127], v[128:131], v[160:163], v[124:127]
	v_mfma_f32_16x16x32_bf16 v[120:123], v[136:139], v[160:163], v[120:123]
	v_mfma_f32_16x16x32_bf16 v[108:111], v[128:131], v[178:181], v[108:111]
	v_mfma_f32_16x16x32_bf16 v[104:107], v[136:139], v[178:181], v[104:107]
	v_mfma_f32_16x16x32_bf16 v[92:95], v[128:131], v[186:189], v[92:95]
	v_mfma_f32_16x16x32_bf16 v[88:91], v[136:139], v[186:189], v[88:91]
	v_mfma_f32_16x16x32_bf16 v[76:79], v[128:131], v[202:205], v[76:79]
	v_mfma_f32_16x16x32_bf16 v[72:75], v[136:139], v[202:205], v[72:75]
	v_mfma_f32_16x16x32_bf16 v[124:127], v[132:135], v[164:167], v[124:127]
	v_mfma_f32_16x16x32_bf16 v[120:123], v[140:143], v[164:167], v[120:123]
	v_mfma_f32_16x16x32_bf16 v[108:111], v[132:135], v[182:185], v[108:111]
	v_mfma_f32_16x16x32_bf16 v[104:107], v[140:143], v[182:185], v[104:107]
	v_mfma_f32_16x16x32_bf16 v[92:95], v[132:135], v[198:201], v[92:95]
	v_mfma_f32_16x16x32_bf16 v[88:91], v[140:143], v[198:201], v[88:91]
	v_mfma_f32_16x16x32_bf16 v[76:79], v[132:135], v[206:209], v[76:79]
	v_mfma_f32_16x16x32_bf16 v[72:75], v[140:143], v[206:209], v[72:75]
	s_setprio 0
	s_setprio 1
	v_mfma_f32_16x16x32_bf16 v[116:119], v[144:147], v[160:163], v[116:119]
	v_mfma_f32_16x16x32_bf16 v[112:115], v[152:155], v[160:163], v[112:115]
	v_mfma_f32_16x16x32_bf16 v[100:103], v[144:147], v[178:181], v[100:103]
	v_mfma_f32_16x16x32_bf16 v[96:99], v[152:155], v[178:181], v[96:99]
	v_mfma_f32_16x16x32_bf16 v[84:87], v[144:147], v[186:189], v[84:87]
	v_mfma_f32_16x16x32_bf16 v[80:83], v[152:155], v[186:189], v[80:83]
	v_mfma_f32_16x16x32_bf16 v[68:71], v[144:147], v[202:205], v[68:71]
	v_mfma_f32_16x16x32_bf16 v[64:67], v[152:155], v[202:205], v[64:67]
	v_mfma_f32_16x16x32_bf16 v[116:119], v[148:151], v[164:167], v[116:119]
	v_mfma_f32_16x16x32_bf16 v[112:115], v[156:159], v[164:167], v[112:115]
	v_mfma_f32_16x16x32_bf16 v[100:103], v[148:151], v[182:185], v[100:103]
	v_mfma_f32_16x16x32_bf16 v[96:99], v[156:159], v[182:185], v[96:99]
	v_mfma_f32_16x16x32_bf16 v[84:87], v[148:151], v[198:201], v[84:87]
	v_mfma_f32_16x16x32_bf16 v[80:83], v[156:159], v[198:201], v[80:83]
	v_mfma_f32_16x16x32_bf16 v[68:71], v[148:151], v[206:209], v[68:71]
	v_mfma_f32_16x16x32_bf16 v[64:67], v[156:159], v[206:209], v[64:67]
	s_setprio 0
	s_barrier
; #define PG8_STAGE(bufoff, gbase, voff) do { _Pragma("unroll") for (int _i = 0; _i < 2; ++_i) \
;         __builtin_amdgcn_global_load_lds((const unsigned*)((const char*)(gbase) + (voff)[_i]), (LAS unsigned*)(lds + (bufoff) + ldsw + _i * 8192), 16, 0, 0); } while (0)
; #define PG8_LDA(dst, b, h) do { _Pragma("unroll") for (int m = 0; m < 4; ++m) _Pragma("unroll") for (int k = 0; k < 2; ++k) dst[m][k] = *(const LAS bf16x8*)(lds + PG8_SA(b, h) + aoff + m * 2048 + k * 1024); } while (0)
; #define PG8_MMA(ai, bj, At, Bt) do { __builtin_amdgcn_s_setprio(1); _Pragma("unroll") for (int m = 0; m < 4; ++m) _Pragma("unroll") for (int n = 0; n < 2; ++n) _Pragma("unroll") for (int k = 0; k < 2; ++k) \
;         acc[ai][bj][m][n] = __builtin_amdgcn_mfma_f32_16x16x32_bf16(Bt[n][k], At[m][k], acc[ai][bj][m][n], 0, 0, 0); __builtin_amdgcn_s_setprio(0); } while (0)
; #define PG8_WAIT_V(n) asm volatile("s_waitcnt vmcnt(" #n ")" ::: "memory")
; #define PG8_WAIT_L(n) asm volatile("s_waitcnt lgkmcnt(" #n ")" ::: "memory")
; #define PG8_BAR __builtin_amdgcn_s_barrier()
; #define PG8_SCHED __builtin_amdgcn_sched_barrier(0)
; template <class Epi, class Sched, bool ALIGN_EPI, bool SP2, bool PERMA = false>
; __device__ __forceinline__ void gemm_phase(LAS unsigned char* lds, const int tid, const int lda, const int ldb, const Sched& S, const Epi& E) {
;     ...
;             PG8_LDA(At, 1, 1); PG8_STAGE(PG8_SB(1, 0), b3, voffB); PG8_STAGE(PG8_SB(1, 1), b3 + hsB, voffB); PG8_STAGE(PG8_SA(1, 0), a3, voffA);
;             PG8_WAIT_V(8); PG8_WAIT_L(0); PG8_BAR; PG8_MMA(1, 0, At, B0); PG8_MMA(1, 1, At, B1); PG8_BAR; PG8_SCHED;
	s_add_i32 s10, s60, s49
	v_lshl_add_u64 v[190:191], v[190:191], 0, s[54:55]
	s_mov_b32 m0, s10
	ds_read_b128 v[160:163], v249 offset:49152
	ds_read_b128 v[164:167], v249 offset:50176
	ds_read_b128 v[178:181], v249 offset:51200
	ds_read_b128 v[182:185], v249 offset:52224
	ds_read_b128 v[186:189], v249 offset:53248
	ds_read_b128 v[198:201], v249 offset:54272
	ds_read_b128 v[202:205], v249 offset:55296
	ds_read_b128 v[206:209], v249 offset:56320
	global_load_lds_dwordx4 v[190:191], off
	s_add_i32 m0, s10, 0x2000
	s_add_u32 s8, s8, 0x60080
	v_lshl_add_u64 v[190:191], v[210:211], 0, s[54:55]
	s_addc_u32 s9, s9, 0
	s_add_i32 s10, s61, s49
	global_load_lds_dwordx4 v[190:191], off
	v_lshl_add_u64 v[190:191], s[8:9], 0, v[192:193]
	s_mov_b32 m0, s10
	s_nop 0
	global_load_lds_dwordx4 v[190:191], off
	v_lshl_add_u64 v[190:191], s[8:9], 0, v[172:173]
	s_add_i32 m0, s10, 0x2000
	s_nop 0
	global_load_lds_dwordx4 v[190:191], off
	v_lshl_add_u64 v[190:191], v[212:213], 0, s[54:55]
	s_mov_b32 m0, s94
	s_nop 0
	global_load_lds_dwordx4 v[190:191], off
	v_lshl_add_u64 v[190:191], v[214:215], 0, s[54:55]
	s_mov_b32 m0, s95
	s_nop 0
	global_load_lds_dwordx4 v[190:191], off
	s_waitcnt vmcnt(8)
	s_waitcnt lgkmcnt(0)
	s_barrier
	s_setprio 1
	s_waitcnt lgkmcnt(0)
	v_mfma_f32_16x16x32_bf16 v[60:63], v[128:131], v[160:163], v[60:63]
	v_mfma_f32_16x16x32_bf16 v[56:59], v[136:139], v[160:163], v[56:59]
	v_mfma_f32_16x16x32_bf16 v[44:47], v[128:131], v[178:181], v[44:47]
	v_mfma_f32_16x16x32_bf16 v[40:43], v[136:139], v[178:181], v[40:43]
	v_mfma_f32_16x16x32_bf16 v[28:31], v[128:131], v[186:189], v[28:31]
	v_mfma_f32_16x16x32_bf16 v[24:27], v[136:139], v[186:189], v[24:27]
	v_mfma_f32_16x16x32_bf16 v[12:15], v[128:131], v[202:205], v[12:15]
	v_mfma_f32_16x16x32_bf16 v[8:11], v[136:139], v[202:205], v[8:11]
	v_mfma_f32_16x16x32_bf16 v[60:63], v[132:135], v[164:167], v[60:63]
	v_mfma_f32_16x16x32_bf16 v[56:59], v[140:143], v[164:167], v[56:59]
	v_mfma_f32_16x16x32_bf16 v[44:47], v[132:135], v[182:185], v[44:47]
	v_mfma_f32_16x16x32_bf16 v[40:43], v[140:143], v[182:185], v[40:43]
	v_mfma_f32_16x16x32_bf16 v[28:31], v[132:135], v[198:201], v[28:31]
	v_mfma_f32_16x16x32_bf16 v[24:27], v[140:143], v[198:201], v[24:27]
	v_mfma_f32_16x16x32_bf16 v[12:15], v[132:135], v[206:209], v[12:15]
	v_mfma_f32_16x16x32_bf16 v[8:11], v[140:143], v[206:209], v[8:11]
	s_setprio 0
	s_setprio 1
	v_mfma_f32_16x16x32_bf16 v[52:55], v[144:147], v[160:163], v[52:55]
	v_mfma_f32_16x16x32_bf16 v[48:51], v[152:155], v[160:163], v[48:51]
	v_mfma_f32_16x16x32_bf16 v[36:39], v[144:147], v[178:181], v[36:39]
	v_mfma_f32_16x16x32_bf16 v[32:35], v[152:155], v[178:181], v[32:35]
	v_mfma_f32_16x16x32_bf16 v[20:23], v[144:147], v[186:189], v[20:23]
	v_mfma_f32_16x16x32_bf16 v[16:19], v[152:155], v[186:189], v[16:19]
	v_mfma_f32_16x16x32_bf16 v[4:7], v[144:147], v[202:205], v[4:7]
	v_mfma_f32_16x16x32_bf16 v[0:3], v[152:155], v[202:205], v[0:3]
	v_mfma_f32_16x16x32_bf16 v[52:55], v[148:151], v[164:167], v[52:55]
	v_mfma_f32_16x16x32_bf16 v[48:51], v[156:159], v[164:167], v[48:51]
	v_mfma_f32_16x16x32_bf16 v[36:39], v[148:151], v[182:185], v[36:39]
	v_mfma_f32_16x16x32_bf16 v[32:35], v[156:159], v[182:185], v[32:35]
	v_mfma_f32_16x16x32_bf16 v[20:23], v[148:151], v[198:201], v[20:23]
	v_mfma_f32_16x16x32_bf16 v[16:19], v[156:159], v[198:201], v[16:19]
	v_mfma_f32_16x16x32_bf16 v[4:7], v[148:151], v[206:209], v[4:7]
	v_mfma_f32_16x16x32_bf16 v[0:3], v[156:159], v[206:209], v[0:3]
	s_setprio 0
	s_barrier
	s_add_u32 vcc_lo, vcc_lo, 0x100
	s_addc_u32 vcc_hi, vcc_hi, 0
	s_add_u32 s0, s0, 0x100
	s_addc_u32 s1, s1, 0
	s_cmp_ge_i32 s21, s13
	s_mov_b32 s8, s21
	s_cbranch_scc1 .Lgemm3_kdone

; #define PG8_BAR __builtin_amdgcn_s_barrier()
; template <class Epi, class Sched, bool ALIGN_EPI, bool SP2, bool PERMA = false>
; __device__ __forceinline__ void gemm_phase(LAS unsigned char* lds, const int tid, const int lda, const int ldb, const Sched& S, const Epi& E) {
;     ...
;         if constexpr (ALIGN_EPI) { if (wr == 0) PG8_BAR; }
.Lgemm3_kdone:
	v_readlane_b32 s0, v254, 49
	v_readlane_b32 s1, v254, 50
	s_and_b64 vcc, exec, s[0:1]
	s_cbranch_vccz .LBB0_266
	s_barrier

; #define PG8_STAGE(bufoff, gbase, voff) do { _Pragma("unroll") for (int _i = 0; _i < 2; ++_i) \
;         __builtin_amdgcn_global_load_lds((const unsigned*)((const char*)(gbase) + (voff)[_i]), (LAS unsigned*)(lds + (bufoff) + ldsw + _i * 8192), 16, 0, 0); } while (0)
; #define PG8_LDA(dst, b, h) do { _Pragma("unroll") for (int m = 0; m < 4; ++m) _Pragma("unroll") for (int k = 0; k < 2; ++k) dst[m][k] = *(const LAS bf16x8*)(lds + PG8_SA(b, h) + aoff + m * 2048 + k * 1024); } while (0)
; #define PG8_LDB(dst, b, h) do { _Pragma("unroll") for (int n = 0; n < 2; ++n) _Pragma("unroll") for (int k = 0; k < 2; ++k) dst[n][k] = *(const LAS bf16x8*)(lds + PG8_SB(b, h) + boff + n * 2048 + k * 1024); } while (0)
; #define PG8_MMA(ai, bj, At, Bt) do { __builtin_amdgcn_s_setprio(1); _Pragma("unroll") for (int m = 0; m < 4; ++m) _Pragma("unroll") for (int n = 0; n < 2; ++n) _Pragma("unroll") for (int k = 0; k < 2; ++k) \
;         acc[ai][bj][m][n] = __builtin_amdgcn_mfma_f32_16x16x32_bf16(Bt[n][k], At[m][k], acc[ai][bj][m][n], 0, 0, 0); __builtin_amdgcn_s_setprio(0); } while (0)
; #define PG8_WAIT_V(n) asm volatile("s_waitcnt vmcnt(" #n ")" ::: "memory")
; #define PG8_WAIT_L(n) asm volatile("s_waitcnt lgkmcnt(" #n ")" ::: "memory")
; template <class Epi, class Sched, bool ALIGN_EPI, bool SP2, bool PERMA = false>
; __device__ __forceinline__ void gemm_phase(LAS unsigned char* lds, const int tid, const int lda, const int ldb, const Sched& S, const Epi& E) {
;     ...
;         const char* nA = has_next ? (const char*)nxt.A : cA; const char* nB = has_next ? (const char*)nxt.B : cB;
;         const int nt = cur.nt;
;         for (int t = 0; t < nt; t += 2) {
;             const bool last = (t == nt - 2);
;             const char* a1 = cA + (size_t)(t + 1) * kstep;
;             const char* a2 = last ? nA : cA + (size_t)(t + 2) * kstep; const char* b2 = last ? nB : cB + (size_t)(t + 2) * kstep;
;             const char* a3 = a2 + kstep; const char* b3 = b2 + kstep;
;             if constexpr (SP2) {
;             PG8_LDB(B0, 0, 0); PG8_LDB(B1, 0, 1); PG8_SCHED; PG8_LDA(At, 0, 0); PG8_STAGE(PG8_SA(1, 1), a1 + hsA, voffA);
;             PG8_WAIT_V(8); PG8_WAIT_L(0); PG8_BAR; PG8_MMA(0, 0, At, B0); PG8_MMA(0, 1, At, B1); PG8_BAR; PG8_SCHED;
;             PG8_LDA(At, 0, 1); PG8_STAGE(PG8_SB(0, 0), b2, voffB); PG8_STAGE(PG8_SB(0, 1), b2 + hsB, voffB); PG8_STAGE(PG8_SA(0, 0), a2, voffA);
.LBB0_440:
	s_add_u32 s3, s18, 0x100
	v_mov_b32_e32 v0, 0
	s_addc_u32 s22, s19, 0
	s_mov_b32 s23, -2
	s_add_u32 s18, s16, 0x100
	s_addc_u32 s19, s17, 0
	s_add_i32 s33, 0, 0x10000
	s_cmp_eq_u32 s23, 8
	s_cselect_b32 s25, s11, s19
	s_cselect_b32 s24, s10, s18
	s_cselect_b32 s21, s15, s22
	s_cselect_b32 s20, s14, s3
	s_add_i32 s50, 0, 0x14000
	v_add_u32_e32 v150, s33, v140
	v_add_u32_e32 v166, s50, v140
	ds_read_b128 v[134:137], v150
	ds_read_b128 v[142:145], v150 offset:1024
	ds_read_b128 v[146:149], v150 offset:2048
	ds_read_b128 v[150:153], v150 offset:3072
	ds_read_b128 v[154:157], v166
	ds_read_b128 v[158:161], v166 offset:1024
	ds_read_b128 v[162:165], v166 offset:2048
	ds_read_b128 v[166:169], v166 offset:3072
	v_lshl_add_u64 v[190:191], s[16:17], 0, v[132:133]
	s_add_i32 m0, s31, 0xc000
	ds_read_b128 v[170:173], v141
	ds_read_b128 v[174:177], v141 offset:1024
	ds_read_b128 v[178:181], v141 offset:2048
	ds_read_b128 v[182:185], v141 offset:3072
	ds_read_b128 v[186:189], v141 offset:4096
	ds_read_b128 v[198:201], v141 offset:5120
	ds_read_b128 v[202:205], v141 offset:6144
	ds_read_b128 v[206:209], v141 offset:7168
	global_load_lds_dwordx4 v[190:191], off
	v_lshl_add_u64 v[190:191], s[16:17], 0, v[130:131]
	s_add_i32 m0, s31, 0xe000
	s_nop 0
	global_load_lds_dwordx4 v[190:191], off
	s_waitcnt vmcnt(8)
	s_waitcnt lgkmcnt(0)
	s_barrier
	s_setprio 1
	s_waitcnt lgkmcnt(0)
	v_mfma_f32_16x16x32_bf16 v[124:127], v[134:137], v[170:173], 0
	v_mfma_f32_16x16x32_bf16 v[120:123], v[146:149], v[170:173], 0
	v_mfma_f32_16x16x32_bf16 v[108:111], v[134:137], v[178:181], 0
	v_mfma_f32_16x16x32_bf16 v[104:107], v[146:149], v[178:181], 0
	v_mfma_f32_16x16x32_bf16 v[92:95], v[134:137], v[186:189], 0
	v_mfma_f32_16x16x32_bf16 v[88:91], v[146:149], v[186:189], 0
	v_mfma_f32_16x16x32_bf16 v[76:79], v[134:137], v[202:205], 0
	v_mfma_f32_16x16x32_bf16 v[72:75], v[146:149], v[202:205], 0
	v_mfma_f32_16x16x32_bf16 v[124:127], v[142:145], v[174:177], v[124:127]
	v_mfma_f32_16x16x32_bf16 v[120:123], v[150:153], v[174:177], v[120:123]
	v_mfma_f32_16x16x32_bf16 v[108:111], v[142:145], v[182:185], v[108:111]
	v_mfma_f32_16x16x32_bf16 v[104:107], v[150:153], v[182:185], v[104:107]
	v_mfma_f32_16x16x32_bf16 v[92:95], v[142:145], v[198:201], v[92:95]
	v_mfma_f32_16x16x32_bf16 v[88:91], v[150:153], v[198:201], v[88:91]
	v_mfma_f32_16x16x32_bf16 v[76:79], v[142:145], v[206:209], v[76:79]
	v_mfma_f32_16x16x32_bf16 v[72:75], v[150:153], v[206:209], v[72:75]
	s_setprio 0
	s_setprio 1
	v_mfma_f32_16x16x32_bf16 v[116:119], v[154:157], v[170:173], 0
	v_mfma_f32_16x16x32_bf16 v[112:115], v[162:165], v[170:173], 0
	v_mfma_f32_16x16x32_bf16 v[100:103], v[154:157], v[178:181], 0
	v_mfma_f32_16x16x32_bf16 v[96:99], v[162:165], v[178:181], 0
	v_mfma_f32_16x16x32_bf16 v[84:87], v[154:157], v[186:189], 0
	v_mfma_f32_16x16x32_bf16 v[80:83], v[162:165], v[186:189], 0
	v_mfma_f32_16x16x32_bf16 v[68:71], v[154:157], v[202:205], 0
	v_mfma_f32_16x16x32_bf16 v[64:67], v[162:165], v[202:205], 0
	v_mfma_f32_16x16x32_bf16 v[116:119], v[158:161], v[174:177], v[116:119]
	v_mfma_f32_16x16x32_bf16 v[112:115], v[166:169], v[174:177], v[112:115]
	v_mfma_f32_16x16x32_bf16 v[100:103], v[158:161], v[182:185], v[100:103]
	v_mfma_f32_16x16x32_bf16 v[96:99], v[166:169], v[182:185], v[96:99]
	v_mfma_f32_16x16x32_bf16 v[84:87], v[158:161], v[198:201], v[84:87]
	v_mfma_f32_16x16x32_bf16 v[80:83], v[166:169], v[198:201], v[80:83]
	v_mfma_f32_16x16x32_bf16 v[68:71], v[158:161], v[206:209], v[68:71]
	v_mfma_f32_16x16x32_bf16 v[64:67], v[166:169], v[206:209], v[64:67]
	s_setprio 0
	s_barrier
	s_add_i32 s16, s33, s30
	v_lshl_add_u64 v[190:191], s[20:21], 0, v[192:193]
	s_mov_b32 m0, s16
	ds_read_b128 v[170:173], v141 offset:16384
	ds_read_b128 v[174:177], v141 offset:17408
	ds_read_b128 v[178:181], v141 offset:18432
	ds_read_b128 v[182:185], v141 offset:19456
	ds_read_b128 v[186:189], v141 offset:20480
	ds_read_b128 v[198:201], v141 offset:21504
	ds_read_b128 v[202:205], v141 offset:22528
	ds_read_b128 v[206:209], v141 offset:23552
	global_load_lds_dwordx4 v[190:191], off
	s_add_i32 m0, s16, 0x2000
	s_add_u32 s16, s20, 0x30000
	v_lshl_add_u64 v[210:211], s[20:21], 0, v[128:129]
	s_addc_u32 s17, s21, 0
	s_add_i32 s33, s50, s30
	global_load_lds_dwordx4 v[210:211], off
	v_lshl_add_u64 v[212:213], s[16:17], 0, v[192:193]
	s_mov_b32 m0, s33
	v_lshl_add_u64 v[214:215], s[24:25], 0, v[128:129]
	global_load_lds_dwordx4 v[212:213], off
	v_lshl_add_u64 v[212:213], s[16:17], 0, v[128:129]
	s_add_i32 m0, s33, 0x2000
	s_nop 0
	global_load_lds_dwordx4 v[212:213], off
	v_lshl_add_u64 v[212:213], s[24:25], 0, v[192:193]
	s_mov_b32 m0, s31
	s_nop 0
	global_load_lds_dwordx4 v[212:213], off
	s_mov_b32 m0, s34
	s_nop 0
	global_load_lds_dwordx4 v[214:215], off
	s_waitcnt vmcnt(8)
	s_waitcnt lgkmcnt(0)
	s_barrier
; #define PG8_STAGE(bufoff, gbase, voff) do { _Pragma("unroll") for (int _i = 0; _i < 2; ++_i) \
;         __builtin_amdgcn_global_load_lds((const unsigned*)((const char*)(gbase) + (voff)[_i]), (LAS unsigned*)(lds + (bufoff) + ldsw + _i * 8192), 16, 0, 0); } while (0)
; #define PG8_LDA(dst, b, h) do { _Pragma("unroll") for (int m = 0; m < 4; ++m) _Pragma("unroll") for (int k = 0; k < 2; ++k) dst[m][k] = *(const LAS bf16x8*)(lds + PG8_SA(b, h) + aoff + m * 2048 + k * 1024); } while (0)
; #define PG8_LDB(dst, b, h) do { _Pragma("unroll") for (int n = 0; n < 2; ++n) _Pragma("unroll") for (int k = 0; k < 2; ++k) dst[n][k] = *(const LAS bf16x8*)(lds + PG8_SB(b, h) + boff + n * 2048 + k * 1024); } while (0)
; #define PG8_MMA(ai, bj, At, Bt) do { __builtin_amdgcn_s_setprio(1); _Pragma("unroll") for (int m = 0; m < 4; ++m) _Pragma("unroll") for (int n = 0; n < 2; ++n) _Pragma("unroll") for (int k = 0; k < 2; ++k) \
;         acc[ai][bj][m][n] = __builtin_amdgcn_mfma_f32_16x16x32_bf16(Bt[n][k], At[m][k], acc[ai][bj][m][n], 0, 0, 0); __builtin_amdgcn_s_setprio(0); } while (0)
; #define PG8_WAIT_V(n) asm volatile("s_waitcnt vmcnt(" #n ")" ::: "memory")
; #define PG8_WAIT_L(n) asm volatile("s_waitcnt lgkmcnt(" #n ")" ::: "memory")
; #define PG8_BAR __builtin_amdgcn_s_barrier()
; #define PG8_SCHED __builtin_amdgcn_sched_barrier(0)
; template <class Epi, class Sched, bool ALIGN_EPI, bool SP2, bool PERMA = false>
; __device__ __forceinline__ void gemm_phase(LAS unsigned char* lds, const int tid, const int lda, const int ldb, const Sched& S, const Epi& E) {
;     ...
;             PG8_WAIT_V(8); PG8_WAIT_L(0); PG8_BAR; PG8_MMA(1, 0, At, B0); PG8_MMA(1, 1, At, B1); PG8_BAR; PG8_SCHED;
;             PG8_LDB(B0, 1, 0); PG8_LDB(B1, 1, 1); PG8_SCHED; PG8_LDA(At, 1, 0); PG8_STAGE(PG8_SA(0, 1), a2 + hsA, voffA);
;             PG8_WAIT_V(8); PG8_WAIT_L(0); PG8_BAR; PG8_MMA(0, 0, At, B0); PG8_MMA(0, 1, At, B1); PG8_BAR; PG8_SCHED;
	s_setprio 1
	s_waitcnt lgkmcnt(0)
	v_mfma_f32_16x16x32_bf16 v[60:63], v[134:137], v[170:173], 0
	v_mfma_f32_16x16x32_bf16 v[56:59], v[146:149], v[170:173], 0
	v_mfma_f32_16x16x32_bf16 v[44:47], v[134:137], v[178:181], 0
	v_mfma_f32_16x16x32_bf16 v[40:43], v[146:149], v[178:181], 0
	v_mfma_f32_16x16x32_bf16 v[28:31], v[134:137], v[186:189], 0
	v_mfma_f32_16x16x32_bf16 v[24:27], v[146:149], v[186:189], 0
	v_mfma_f32_16x16x32_bf16 v[12:15], v[134:137], v[202:205], 0
	v_mfma_f32_16x16x32_bf16 v[8:11], v[146:149], v[202:205], 0
	v_mfma_f32_16x16x32_bf16 v[60:63], v[142:145], v[174:177], v[60:63]
	v_mfma_f32_16x16x32_bf16 v[56:59], v[150:153], v[174:177], v[56:59]
	v_mfma_f32_16x16x32_bf16 v[44:47], v[142:145], v[182:185], v[44:47]
	v_mfma_f32_16x16x32_bf16 v[40:43], v[150:153], v[182:185], v[40:43]
	v_mfma_f32_16x16x32_bf16 v[28:31], v[142:145], v[198:201], v[28:31]
	v_mfma_f32_16x16x32_bf16 v[24:27], v[150:153], v[198:201], v[24:27]
	v_mfma_f32_16x16x32_bf16 v[12:15], v[142:145], v[206:209], v[12:15]
	v_mfma_f32_16x16x32_bf16 v[8:11], v[150:153], v[206:209], v[8:11]
	s_setprio 0
	s_setprio 1
	v_mfma_f32_16x16x32_bf16 v[52:55], v[154:157], v[170:173], 0
	v_mfma_f32_16x16x32_bf16 v[48:51], v[162:165], v[170:173], 0
	v_mfma_f32_16x16x32_bf16 v[36:39], v[154:157], v[178:181], 0
	v_mfma_f32_16x16x32_bf16 v[32:35], v[162:165], v[178:181], 0
	v_mfma_f32_16x16x32_bf16 v[20:23], v[154:157], v[186:189], 0
	v_mfma_f32_16x16x32_bf16 v[16:19], v[162:165], v[186:189], 0
	v_mfma_f32_16x16x32_bf16 v[4:7], v[154:157], v[202:205], 0
	v_mfma_f32_16x16x32_bf16 v[0:3], v[162:165], v[202:205], 0
	v_mfma_f32_16x16x32_bf16 v[52:55], v[158:161], v[174:177], v[52:55]
	v_mfma_f32_16x16x32_bf16 v[48:51], v[166:169], v[174:177], v[48:51]
	v_mfma_f32_16x16x32_bf16 v[36:39], v[158:161], v[182:185], v[36:39]
	v_mfma_f32_16x16x32_bf16 v[32:35], v[166:169], v[182:185], v[32:35]
	v_mfma_f32_16x16x32_bf16 v[20:23], v[158:161], v[198:201], v[20:23]
	v_mfma_f32_16x16x32_bf16 v[16:19], v[166:169], v[198:201], v[16:19]
	v_mfma_f32_16x16x32_bf16 v[4:7], v[158:161], v[206:209], v[4:7]
	v_mfma_f32_16x16x32_bf16 v[0:3], v[166:169], v[206:209], v[0:3]
	s_setprio 0
	s_barrier
	s_add_i32 s33, 0, 0x18000
	s_add_i32 s50, 0, 0x1c000
	v_add_u32_e32 v150, s33, v140
	v_add_u32_e32 v166, s50, v140
	ds_read_b128 v[134:137], v150
	ds_read_b128 v[142:145], v150 offset:1024
	ds_read_b128 v[146:149], v150 offset:2048
	ds_read_b128 v[150:153], v150 offset:3072
	ds_read_b128 v[154:157], v166
	ds_read_b128 v[158:161], v166 offset:1024
	ds_read_b128 v[162:165], v166 offset:2048
	ds_read_b128 v[166:169], v166 offset:3072
	s_add_u32 s16, s24, 0x30000
	s_addc_u32 s17, s25, 0
	s_mov_b32 m0, s35
	v_lshl_add_u64 v[216:217], s[16:17], 0, v[192:193]
	ds_read_b128 v[170:173], v141 offset:32768
	ds_read_b128 v[174:177], v141 offset:33792
	ds_read_b128 v[178:181], v141 offset:34816
	ds_read_b128 v[182:185], v141 offset:35840
	ds_read_b128 v[186:189], v141 offset:36864
	ds_read_b128 v[198:201], v141 offset:37888
	ds_read_b128 v[202:205], v141 offset:38912
	ds_read_b128 v[206:209], v141 offset:39936
	global_load_lds_dwordx4 v[216:217], off
	v_lshl_add_u64 v[216:217], s[16:17], 0, v[128:129]
	s_mov_b32 m0, s49
	s_nop 0
	global_load_lds_dwordx4 v[216:217], off
	s_waitcnt vmcnt(8)
	s_waitcnt lgkmcnt(0)
	s_barrier
	s_setprio 1
	s_waitcnt lgkmcnt(0)
	v_mfma_f32_16x16x32_bf16 v[124:127], v[134:137], v[170:173], v[124:127]
	v_mfma_f32_16x16x32_bf16 v[120:123], v[146:149], v[170:173], v[120:123]
	v_mfma_f32_16x16x32_bf16 v[108:111], v[134:137], v[178:181], v[108:111]
	v_mfma_f32_16x16x32_bf16 v[104:107], v[146:149], v[178:181], v[104:107]
	v_mfma_f32_16x16x32_bf16 v[92:95], v[134:137], v[186:189], v[92:95]
	v_mfma_f32_16x16x32_bf16 v[88:91], v[146:149], v[186:189], v[88:91]
	v_mfma_f32_16x16x32_bf16 v[76:79], v[134:137], v[202:205], v[76:79]
	v_mfma_f32_16x16x32_bf16 v[72:75], v[146:149], v[202:205], v[72:75]
	v_mfma_f32_16x16x32_bf16 v[124:127], v[142:145], v[174:177], v[124:127]
	v_mfma_f32_16x16x32_bf16 v[120:123], v[150:153], v[174:177], v[120:123]
	v_mfma_f32_16x16x32_bf16 v[108:111], v[142:145], v[182:185], v[108:111]
	v_mfma_f32_16x16x32_bf16 v[104:107], v[150:153], v[182:185], v[104:107]
	v_mfma_f32_16x16x32_bf16 v[92:95], v[142:145], v[198:201], v[92:95]
	v_mfma_f32_16x16x32_bf16 v[88:91], v[150:153], v[198:201], v[88:91]
	v_mfma_f32_16x16x32_bf16 v[76:79], v[142:145], v[206:209], v[76:79]
	v_mfma_f32_16x16x32_bf16 v[72:75], v[150:153], v[206:209], v[72:75]
	s_setprio 0
	s_setprio 1
	v_mfma_f32_16x16x32_bf16 v[116:119], v[154:157], v[170:173], v[116:119]
	v_mfma_f32_16x16x32_bf16 v[112:115], v[162:165], v[170:173], v[112:115]
	v_mfma_f32_16x16x32_bf16 v[100:103], v[154:157], v[178:181], v[100:103]
	v_mfma_f32_16x16x32_bf16 v[96:99], v[162:165], v[178:181], v[96:99]
	v_mfma_f32_16x16x32_bf16 v[84:87], v[154:157], v[186:189], v[84:87]
	v_mfma_f32_16x16x32_bf16 v[80:83], v[162:165], v[186:189], v[80:83]
	v_mfma_f32_16x16x32_bf16 v[68:71], v[154:157], v[202:205], v[68:71]
	v_mfma_f32_16x16x32_bf16 v[64:67], v[162:165], v[202:205], v[64:67]
	v_mfma_f32_16x16x32_bf16 v[116:119], v[158:161], v[174:177], v[116:119]
	v_mfma_f32_16x16x32_bf16 v[112:115], v[166:169], v[174:177], v[112:115]
	v_mfma_f32_16x16x32_bf16 v[100:103], v[158:161], v[182:185], v[100:103]
	v_mfma_f32_16x16x32_bf16 v[96:99], v[166:169], v[182:185], v[96:99]
	v_mfma_f32_16x16x32_bf16 v[84:87], v[158:161], v[198:201], v[84:87]
	v_mfma_f32_16x16x32_bf16 v[80:83], v[166:169], v[198:201], v[80:83]
	v_mfma_f32_16x16x32_bf16 v[68:71], v[158:161], v[206:209], v[68:71]
	v_mfma_f32_16x16x32_bf16 v[64:67], v[166:169], v[206:209], v[64:67]
	s_setprio 0
	s_barrier
; #define PG8_STAGE(bufoff, gbase, voff) do { _Pragma("unroll") for (int _i = 0; _i < 2; ++_i) \
;         __builtin_amdgcn_global_load_lds((const unsigned*)((const char*)(gbase) + (voff)[_i]), (LAS unsigned*)(lds + (bufoff) + ldsw + _i * 8192), 16, 0, 0); } while (0)
; #define PG8_LDA(dst, b, h) do { _Pragma("unroll") for (int m = 0; m < 4; ++m) _Pragma("unroll") for (int k = 0; k < 2; ++k) dst[m][k] = *(const LAS bf16x8*)(lds + PG8_SA(b, h) + aoff + m * 2048 + k * 1024); } while (0)
; #define PG8_MMA(ai, bj, At, Bt) do { __builtin_amdgcn_s_setprio(1); _Pragma("unroll") for (int m = 0; m < 4; ++m) _Pragma("unroll") for (int n = 0; n < 2; ++n) _Pragma("unroll") for (int k = 0; k < 2; ++k) \
;         acc[ai][bj][m][n] = __builtin_amdgcn_mfma_f32_16x16x32_bf16(Bt[n][k], At[m][k], acc[ai][bj][m][n], 0, 0, 0); __builtin_amdgcn_s_setprio(0); } while (0)
; #define PG8_WAIT_V(n) asm volatile("s_waitcnt vmcnt(" #n ")" ::: "memory")
; #define PG8_WAIT_L(n) asm volatile("s_waitcnt lgkmcnt(" #n ")" ::: "memory")
; #define PG8_BAR __builtin_amdgcn_s_barrier()
; #define PG8_SCHED __builtin_amdgcn_sched_barrier(0)
; template <class Epi, class Sched, bool ALIGN_EPI, bool SP2, bool PERMA = false>
; __device__ __forceinline__ void gemm_phase(LAS unsigned char* lds, const int tid, const int lda, const int ldb, const Sched& S, const Epi& E) {
;     ...
;             PG8_LDA(At, 1, 1); PG8_STAGE(PG8_SB(1, 0), b3, voffB); PG8_STAGE(PG8_SB(1, 1), b3 + hsB, voffB); PG8_STAGE(PG8_SA(1, 0), a3, voffA);
;             PG8_WAIT_V(8); PG8_WAIT_L(0); PG8_BAR; PG8_MMA(1, 0, At, B0); PG8_MMA(1, 1, At, B1); PG8_BAR; PG8_SCHED;
	s_add_i32 s16, s33, s30
	v_lshl_add_u64 v[190:191], v[190:191], 0, s[54:55]
	s_mov_b32 m0, s16
	ds_read_b128 v[170:173], v141 offset:49152
	ds_read_b128 v[174:177], v141 offset:50176
	ds_read_b128 v[178:181], v141 offset:51200
	ds_read_b128 v[182:185], v141 offset:52224
	ds_read_b128 v[186:189], v141 offset:53248
	ds_read_b128 v[198:201], v141 offset:54272
	ds_read_b128 v[202:205], v141 offset:55296
	ds_read_b128 v[206:209], v141 offset:56320
	global_load_lds_dwordx4 v[190:191], off
	s_add_i32 m0, s16, 0x2000
	s_add_u32 s16, s20, 0x30080
	v_lshl_add_u64 v[190:191], v[210:211], 0, s[54:55]
	s_addc_u32 s17, s21, 0
	s_add_i32 s20, s50, s30
	global_load_lds_dwordx4 v[190:191], off
	v_lshl_add_u64 v[190:191], s[16:17], 0, v[192:193]
	s_mov_b32 m0, s20
	s_nop 0
	global_load_lds_dwordx4 v[190:191], off
	v_lshl_add_u64 v[190:191], s[16:17], 0, v[128:129]
	s_add_i32 m0, s20, 0x2000
	s_nop 0
	global_load_lds_dwordx4 v[190:191], off
	v_lshl_add_u64 v[190:191], v[212:213], 0, s[54:55]
	s_mov_b32 m0, s92
	s_nop 0
	global_load_lds_dwordx4 v[190:191], off
	v_lshl_add_u64 v[190:191], v[214:215], 0, s[54:55]
	s_mov_b32 m0, s94
	s_nop 0
	global_load_lds_dwordx4 v[190:191], off
	s_waitcnt vmcnt(8)
	s_waitcnt lgkmcnt(0)
	s_barrier
	s_setprio 1
	s_waitcnt lgkmcnt(0)
	v_mfma_f32_16x16x32_bf16 v[60:63], v[134:137], v[170:173], v[60:63]
	v_mfma_f32_16x16x32_bf16 v[56:59], v[146:149], v[170:173], v[56:59]
	v_mfma_f32_16x16x32_bf16 v[44:47], v[134:137], v[178:181], v[44:47]
	v_mfma_f32_16x16x32_bf16 v[40:43], v[146:149], v[178:181], v[40:43]
	v_mfma_f32_16x16x32_bf16 v[28:31], v[134:137], v[186:189], v[28:31]
	v_mfma_f32_16x16x32_bf16 v[24:27], v[146:149], v[186:189], v[24:27]
	v_mfma_f32_16x16x32_bf16 v[12:15], v[134:137], v[202:205], v[12:15]
	v_mfma_f32_16x16x32_bf16 v[8:11], v[146:149], v[202:205], v[8:11]
	v_mfma_f32_16x16x32_bf16 v[60:63], v[142:145], v[174:177], v[60:63]
	v_mfma_f32_16x16x32_bf16 v[56:59], v[150:153], v[174:177], v[56:59]
	v_mfma_f32_16x16x32_bf16 v[44:47], v[142:145], v[182:185], v[44:47]
	v_mfma_f32_16x16x32_bf16 v[40:43], v[150:153], v[182:185], v[40:43]
	v_mfma_f32_16x16x32_bf16 v[28:31], v[142:145], v[198:201], v[28:31]
	v_mfma_f32_16x16x32_bf16 v[24:27], v[150:153], v[198:201], v[24:27]
	v_mfma_f32_16x16x32_bf16 v[12:15], v[142:145], v[206:209], v[12:15]
	v_mfma_f32_16x16x32_bf16 v[8:11], v[150:153], v[206:209], v[8:11]
	s_setprio 0
	s_setprio 1
	v_mfma_f32_16x16x32_bf16 v[52:55], v[154:157], v[170:173], v[52:55]
	v_mfma_f32_16x16x32_bf16 v[48:51], v[162:165], v[170:173], v[48:51]
	v_mfma_f32_16x16x32_bf16 v[36:39], v[154:157], v[178:181], v[36:39]
	v_mfma_f32_16x16x32_bf16 v[32:35], v[162:165], v[178:181], v[32:35]
	v_mfma_f32_16x16x32_bf16 v[20:23], v[154:157], v[186:189], v[20:23]
	v_mfma_f32_16x16x32_bf16 v[16:19], v[162:165], v[186:189], v[16:19]
	v_mfma_f32_16x16x32_bf16 v[4:7], v[154:157], v[202:205], v[4:7]
	v_mfma_f32_16x16x32_bf16 v[0:3], v[162:165], v[202:205], v[0:3]
	v_mfma_f32_16x16x32_bf16 v[52:55], v[158:161], v[174:177], v[52:55]
	v_mfma_f32_16x16x32_bf16 v[48:51], v[166:169], v[174:177], v[48:51]
	v_mfma_f32_16x16x32_bf16 v[36:39], v[158:161], v[182:185], v[36:39]
	v_mfma_f32_16x16x32_bf16 v[32:35], v[166:169], v[182:185], v[32:35]
	v_mfma_f32_16x16x32_bf16 v[20:23], v[158:161], v[198:201], v[20:23]
	v_mfma_f32_16x16x32_bf16 v[16:19], v[166:169], v[198:201], v[16:19]
	v_mfma_f32_16x16x32_bf16 v[4:7], v[158:161], v[206:209], v[4:7]
	v_mfma_f32_16x16x32_bf16 v[0:3], v[166:169], v[206:209], v[0:3]
	s_setprio 0
	s_barrier
	s_add_i32 s23, s23, 2
	s_add_u32 s3, s3, 0x100
	s_addc_u32 s22, s22, 0
	s_cmp_gt_u32 s23, 9
	s_mov_b64 s[16:17], s[18:19]
	s_cbranch_scc1 .Lgemm5_kdone

; #define PG8_BAR __builtin_amdgcn_s_barrier()
; template <class Epi, class Sched, bool ALIGN_EPI, bool SP2, bool PERMA = false>
; __device__ __forceinline__ void gemm_phase(LAS unsigned char* lds, const int tid, const int lda, const int ldb, const Sched& S, const Epi& E) {
;     ...
;         if constexpr (ALIGN_EPI) { if (wr == 0) PG8_BAR; }
.Lgemm5_kdone:
	s_and_b64 vcc, exec, s[8:9]
	s_cbranch_vccz .LBB0_444
	s_barrier

; #define PG8_STAGE(bufoff, gbase, voff) do { _Pragma("unroll") for (int _i = 0; _i < 2; ++_i) \
;         __builtin_amdgcn_global_load_lds((const unsigned*)((const char*)(gbase) + (voff)[_i]), (LAS unsigned*)(lds + (bufoff) + ldsw + _i * 8192), 16, 0, 0); } while (0)
; #define PG8_LDA(dst, b, h) do { _Pragma("unroll") for (int m = 0; m < 4; ++m) _Pragma("unroll") for (int k = 0; k < 2; ++k) dst[m][k] = *(const LAS bf16x8*)(lds + PG8_SA(b, h) + aoff + m * 2048 + k * 1024); } while (0)
; #define PG8_LDB(dst, b, h) do { _Pragma("unroll") for (int n = 0; n < 2; ++n) _Pragma("unroll") for (int k = 0; k < 2; ++k) dst[n][k] = *(const LAS bf16x8*)(lds + PG8_SB(b, h) + boff + n * 2048 + k * 1024); } while (0)
; #define PG8_MMA(ai, bj, At, Bt) do { __builtin_amdgcn_s_setprio(1); _Pragma("unroll") for (int m = 0; m < 4; ++m) _Pragma("unroll") for (int n = 0; n < 2; ++n) _Pragma("unroll") for (int k = 0; k < 2; ++k) \
;         acc[ai][bj][m][n] = __builtin_amdgcn_mfma_f32_16x16x32_bf16(Bt[n][k], At[m][k], acc[ai][bj][m][n], 0, 0, 0); __builtin_amdgcn_s_setprio(0); } while (0)
; #define PG8_WAIT_V(n) asm volatile("s_waitcnt vmcnt(" #n ")" ::: "memory")
; #define PG8_WAIT_L(n) asm volatile("s_waitcnt lgkmcnt(" #n ")" ::: "memory")
; template <class Epi, class Sched, bool ALIGN_EPI, bool SP2, bool PERMA = false>
; __device__ __forceinline__ void gemm_phase(LAS unsigned char* lds, const int tid, const int lda, const int ldb, const Sched& S, const Epi& E) {
;     ...
;         const char* nA = has_next ? (const char*)nxt.A : cA; const char* nB = has_next ? (const char*)nxt.B : cB;
;         const int nt = cur.nt;
;         for (int t = 0; t < nt; t += 2) {
;             const bool last = (t == nt - 2);
;             const char* a1 = cA + (size_t)(t + 1) * kstep;
;             const char* a2 = last ? nA : cA + (size_t)(t + 2) * kstep; const char* b2 = last ? nB : cB + (size_t)(t + 2) * kstep;
;             const char* a3 = a2 + kstep; const char* b3 = b2 + kstep;
;             if constexpr (SP2) {
;             PG8_LDB(B0, 0, 0); PG8_LDB(B1, 0, 1); PG8_SCHED; PG8_LDA(At, 0, 0); PG8_STAGE(PG8_SA(1, 1), a1 + hsA, voffA);
;             PG8_WAIT_V(8); PG8_WAIT_L(0); PG8_BAR; PG8_MMA(0, 0, At, B0); PG8_MMA(0, 1, At, B1); PG8_BAR; PG8_SCHED;
;             PG8_LDA(At, 0, 1); PG8_STAGE(PG8_SB(0, 0), b2, voffB); PG8_STAGE(PG8_SB(0, 1), b2 + hsB, voffB); PG8_STAGE(PG8_SA(0, 0), a2, voffA);
.LBB0_490:
	s_add_u32 s1, s24, 0x100
	v_mov_b32_e32 v0, 0
	s_addc_u32 s13, s25, 0
	s_mov_b32 s33, -2
	s_add_u32 s24, s20, 0x100
	s_addc_u32 s25, s21, 0
	s_add_i32 s60, 0, 0x10000
	s_cmp_eq_u32 s33, 4
	s_cselect_b32 s29, s15, s25
	s_cselect_b32 s28, s14, s24
	s_cselect_b32 s27, s17, s13
	s_cselect_b32 s26, s16, s1
	s_add_i32 s61, 0, 0x14000
	v_add_u32_e32 v154, s60, v140
	v_add_u32_e32 v170, s61, v140
	ds_read_b128 v[142:145], v154
	ds_read_b128 v[146:149], v154 offset:1024
	ds_read_b128 v[150:153], v154 offset:2048
	ds_read_b128 v[154:157], v154 offset:3072
	ds_read_b128 v[158:161], v170
	ds_read_b128 v[162:165], v170 offset:1024
	ds_read_b128 v[166:169], v170 offset:2048
	ds_read_b128 v[170:173], v170 offset:3072
	v_lshl_add_u64 v[190:191], s[20:21], 0, v[136:137]
	s_add_i32 m0, s31, 0xc000
	ds_read_b128 v[174:177], v141
	ds_read_b128 v[178:181], v141 offset:1024
	ds_read_b128 v[182:185], v141 offset:2048
	ds_read_b128 v[186:189], v141 offset:3072
	ds_read_b128 v[198:201], v141 offset:4096
	ds_read_b128 v[202:205], v141 offset:5120
	ds_read_b128 v[206:209], v141 offset:6144
	ds_read_b128 v[210:213], v141 offset:7168
	global_load_lds_dwordx4 v[190:191], off
	v_lshl_add_u64 v[190:191], s[20:21], 0, v[134:135]
	s_add_i32 m0, s31, 0xe000
	s_nop 0
	global_load_lds_dwordx4 v[190:191], off
	s_waitcnt vmcnt(8)
	s_waitcnt lgkmcnt(0)
	s_barrier
	s_setprio 1
	s_waitcnt lgkmcnt(0)
	v_mfma_f32_16x16x32_bf16 v[124:127], v[142:145], v[174:177], 0
	v_mfma_f32_16x16x32_bf16 v[120:123], v[150:153], v[174:177], 0
	v_mfma_f32_16x16x32_bf16 v[116:119], v[142:145], v[182:185], 0
	v_mfma_f32_16x16x32_bf16 v[112:115], v[150:153], v[182:185], 0
	v_mfma_f32_16x16x32_bf16 v[100:103], v[142:145], v[198:201], 0
	v_mfma_f32_16x16x32_bf16 v[96:99], v[150:153], v[198:201], 0
	v_mfma_f32_16x16x32_bf16 v[84:87], v[142:145], v[206:209], 0
	v_mfma_f32_16x16x32_bf16 v[80:83], v[150:153], v[206:209], 0
	v_mfma_f32_16x16x32_bf16 v[124:127], v[146:149], v[178:181], v[124:127]
	v_mfma_f32_16x16x32_bf16 v[120:123], v[154:157], v[178:181], v[120:123]
	v_mfma_f32_16x16x32_bf16 v[116:119], v[146:149], v[186:189], v[116:119]
	v_mfma_f32_16x16x32_bf16 v[112:115], v[154:157], v[186:189], v[112:115]
	v_mfma_f32_16x16x32_bf16 v[100:103], v[146:149], v[202:205], v[100:103]
	v_mfma_f32_16x16x32_bf16 v[96:99], v[154:157], v[202:205], v[96:99]
	v_mfma_f32_16x16x32_bf16 v[84:87], v[146:149], v[210:213], v[84:87]
	v_mfma_f32_16x16x32_bf16 v[80:83], v[154:157], v[210:213], v[80:83]
	s_setprio 0
	s_setprio 1
	v_mfma_f32_16x16x32_bf16 v[108:111], v[158:161], v[174:177], 0
	v_mfma_f32_16x16x32_bf16 v[104:107], v[166:169], v[174:177], 0
	v_mfma_f32_16x16x32_bf16 v[92:95], v[158:161], v[182:185], 0
	v_mfma_f32_16x16x32_bf16 v[88:91], v[166:169], v[182:185], 0
	v_mfma_f32_16x16x32_bf16 v[76:79], v[158:161], v[198:201], 0
	v_mfma_f32_16x16x32_bf16 v[72:75], v[166:169], v[198:201], 0
	v_mfma_f32_16x16x32_bf16 v[68:71], v[158:161], v[206:209], 0
	v_mfma_f32_16x16x32_bf16 v[64:67], v[166:169], v[206:209], 0
	v_mfma_f32_16x16x32_bf16 v[108:111], v[162:165], v[178:181], v[108:111]
	v_mfma_f32_16x16x32_bf16 v[104:107], v[170:173], v[178:181], v[104:107]
	v_mfma_f32_16x16x32_bf16 v[92:95], v[162:165], v[186:189], v[92:95]
	v_mfma_f32_16x16x32_bf16 v[88:91], v[170:173], v[186:189], v[88:91]
	v_mfma_f32_16x16x32_bf16 v[76:79], v[162:165], v[202:205], v[76:79]
	v_mfma_f32_16x16x32_bf16 v[72:75], v[170:173], v[202:205], v[72:75]
	v_mfma_f32_16x16x32_bf16 v[68:71], v[162:165], v[210:213], v[68:71]
	v_mfma_f32_16x16x32_bf16 v[64:67], v[170:173], v[210:213], v[64:67]
	s_setprio 0
	s_barrier
	s_add_i32 s20, s60, s30
	v_lshl_add_u64 v[190:191], s[26:27], 0, v[192:193]
	s_mov_b32 m0, s20
	ds_read_b128 v[174:177], v141 offset:16384
	ds_read_b128 v[178:181], v141 offset:17408
	ds_read_b128 v[182:185], v141 offset:18432
	ds_read_b128 v[186:189], v141 offset:19456
	ds_read_b128 v[198:201], v141 offset:20480
	ds_read_b128 v[202:205], v141 offset:21504
	ds_read_b128 v[206:209], v141 offset:22528
	ds_read_b128 v[210:213], v141 offset:23552
	global_load_lds_dwordx4 v[190:191], off
	s_add_i32 m0, s20, 0x2000
	s_add_u32 s20, s26, 0x20000
	v_lshl_add_u64 v[214:215], s[26:27], 0, v[128:129]
	s_addc_u32 s21, s27, 0
	s_add_i32 s60, s61, s30
	global_load_lds_dwordx4 v[214:215], off
	v_lshl_add_u64 v[216:217], s[20:21], 0, v[192:193]
	s_mov_b32 m0, s60
	v_lshl_add_u64 v[218:219], s[28:29], 0, v[130:131]
	global_load_lds_dwordx4 v[216:217], off
	v_lshl_add_u64 v[216:217], s[20:21], 0, v[128:129]
	s_add_i32 m0, s60, 0x2000
	s_nop 0
	global_load_lds_dwordx4 v[216:217], off
	v_lshl_add_u64 v[216:217], s[28:29], 0, v[132:133]
	s_mov_b32 m0, s31
	s_nop 0
	global_load_lds_dwordx4 v[216:217], off
	s_mov_b32 m0, s34
	s_nop 0
	global_load_lds_dwordx4 v[218:219], off
	s_waitcnt vmcnt(8)
	s_waitcnt lgkmcnt(0)
	s_barrier
; #define PG8_STAGE(bufoff, gbase, voff) do { _Pragma("unroll") for (int _i = 0; _i < 2; ++_i) \
;         __builtin_amdgcn_global_load_lds((const unsigned*)((const char*)(gbase) + (voff)[_i]), (LAS unsigned*)(lds + (bufoff) + ldsw + _i * 8192), 16, 0, 0); } while (0)
; #define PG8_LDA(dst, b, h) do { _Pragma("unroll") for (int m = 0; m < 4; ++m) _Pragma("unroll") for (int k = 0; k < 2; ++k) dst[m][k] = *(const LAS bf16x8*)(lds + PG8_SA(b, h) + aoff + m * 2048 + k * 1024); } while (0)
; #define PG8_LDB(dst, b, h) do { _Pragma("unroll") for (int n = 0; n < 2; ++n) _Pragma("unroll") for (int k = 0; k < 2; ++k) dst[n][k] = *(const LAS bf16x8*)(lds + PG8_SB(b, h) + boff + n * 2048 + k * 1024); } while (0)
; #define PG8_MMA(ai, bj, At, Bt) do { __builtin_amdgcn_s_setprio(1); _Pragma("unroll") for (int m = 0; m < 4; ++m) _Pragma("unroll") for (int n = 0; n < 2; ++n) _Pragma("unroll") for (int k = 0; k < 2; ++k) \
;         acc[ai][bj][m][n] = __builtin_amdgcn_mfma_f32_16x16x32_bf16(Bt[n][k], At[m][k], acc[ai][bj][m][n], 0, 0, 0); __builtin_amdgcn_s_setprio(0); } while (0)
; #define PG8_WAIT_V(n) asm volatile("s_waitcnt vmcnt(" #n ")" ::: "memory")
; #define PG8_WAIT_L(n) asm volatile("s_waitcnt lgkmcnt(" #n ")" ::: "memory")
; #define PG8_BAR __builtin_amdgcn_s_barrier()
; #define PG8_SCHED __builtin_amdgcn_sched_barrier(0)
; template <class Epi, class Sched, bool ALIGN_EPI, bool SP2, bool PERMA = false>
; __device__ __forceinline__ void gemm_phase(LAS unsigned char* lds, const int tid, const int lda, const int ldb, const Sched& S, const Epi& E) {
;     ...
;             PG8_WAIT_V(8); PG8_WAIT_L(0); PG8_BAR; PG8_MMA(1, 0, At, B0); PG8_MMA(1, 1, At, B1); PG8_BAR; PG8_SCHED;
;             PG8_LDB(B0, 1, 0); PG8_LDB(B1, 1, 1); PG8_SCHED; PG8_LDA(At, 1, 0); PG8_STAGE(PG8_SA(0, 1), a2 + hsA, voffA);
;             PG8_WAIT_V(8); PG8_WAIT_L(0); PG8_BAR; PG8_MMA(0, 0, At, B0); PG8_MMA(0, 1, At, B1); PG8_BAR; PG8_SCHED;
	s_setprio 1
	s_waitcnt lgkmcnt(0)
	v_mfma_f32_16x16x32_bf16 v[60:63], v[142:145], v[174:177], 0
	v_mfma_f32_16x16x32_bf16 v[56:59], v[150:153], v[174:177], 0
	v_mfma_f32_16x16x32_bf16 v[52:55], v[142:145], v[182:185], 0
	v_mfma_f32_16x16x32_bf16 v[48:51], v[150:153], v[182:185], 0
	v_mfma_f32_16x16x32_bf16 v[36:39], v[142:145], v[198:201], 0
	v_mfma_f32_16x16x32_bf16 v[32:35], v[150:153], v[198:201], 0
	v_mfma_f32_16x16x32_bf16 v[20:23], v[142:145], v[206:209], 0
	v_mfma_f32_16x16x32_bf16 v[16:19], v[150:153], v[206:209], 0
	v_mfma_f32_16x16x32_bf16 v[60:63], v[146:149], v[178:181], v[60:63]
	v_mfma_f32_16x16x32_bf16 v[56:59], v[154:157], v[178:181], v[56:59]
	v_mfma_f32_16x16x32_bf16 v[52:55], v[146:149], v[186:189], v[52:55]
	v_mfma_f32_16x16x32_bf16 v[48:51], v[154:157], v[186:189], v[48:51]
	v_mfma_f32_16x16x32_bf16 v[36:39], v[146:149], v[202:205], v[36:39]
	v_mfma_f32_16x16x32_bf16 v[32:35], v[154:157], v[202:205], v[32:35]
	v_mfma_f32_16x16x32_bf16 v[20:23], v[146:149], v[210:213], v[20:23]
	v_mfma_f32_16x16x32_bf16 v[16:19], v[154:157], v[210:213], v[16:19]
	s_setprio 0
	s_setprio 1
	v_mfma_f32_16x16x32_bf16 v[44:47], v[158:161], v[174:177], 0
	v_mfma_f32_16x16x32_bf16 v[40:43], v[166:169], v[174:177], 0
	v_mfma_f32_16x16x32_bf16 v[28:31], v[158:161], v[182:185], 0
	v_mfma_f32_16x16x32_bf16 v[24:27], v[166:169], v[182:185], 0
	v_mfma_f32_16x16x32_bf16 v[12:15], v[158:161], v[198:201], 0
	v_mfma_f32_16x16x32_bf16 v[8:11], v[166:169], v[198:201], 0
	v_mfma_f32_16x16x32_bf16 v[4:7], v[158:161], v[206:209], 0
	v_mfma_f32_16x16x32_bf16 v[0:3], v[166:169], v[206:209], 0
	v_mfma_f32_16x16x32_bf16 v[44:47], v[162:165], v[178:181], v[44:47]
	v_mfma_f32_16x16x32_bf16 v[40:43], v[170:173], v[178:181], v[40:43]
	v_mfma_f32_16x16x32_bf16 v[28:31], v[162:165], v[186:189], v[28:31]
	v_mfma_f32_16x16x32_bf16 v[24:27], v[170:173], v[186:189], v[24:27]
	v_mfma_f32_16x16x32_bf16 v[12:15], v[162:165], v[202:205], v[12:15]
	v_mfma_f32_16x16x32_bf16 v[8:11], v[170:173], v[202:205], v[8:11]
	v_mfma_f32_16x16x32_bf16 v[4:7], v[162:165], v[210:213], v[4:7]
	v_mfma_f32_16x16x32_bf16 v[0:3], v[170:173], v[210:213], v[0:3]
	s_setprio 0
	s_barrier
	s_add_i32 s60, 0, 0x18000
	s_add_i32 s61, 0, 0x1c000
	v_add_u32_e32 v154, s60, v140
	v_add_u32_e32 v170, s61, v140
	ds_read_b128 v[142:145], v154
	ds_read_b128 v[146:149], v154 offset:1024
	ds_read_b128 v[150:153], v154 offset:2048
	ds_read_b128 v[154:157], v154 offset:3072
	ds_read_b128 v[158:161], v170
	ds_read_b128 v[162:165], v170 offset:1024
	ds_read_b128 v[166:169], v170 offset:2048
	ds_read_b128 v[170:173], v170 offset:3072
	s_add_u32 s20, s28, 0x30000
	s_addc_u32 s21, s29, 0
	s_mov_b32 m0, s35
	v_lshl_add_u64 v[220:221], s[20:21], 0, v[132:133]
	ds_read_b128 v[174:177], v141 offset:32768
	ds_read_b128 v[178:181], v141 offset:33792
	ds_read_b128 v[182:185], v141 offset:34816
	ds_read_b128 v[186:189], v141 offset:35840
	ds_read_b128 v[198:201], v141 offset:36864
	ds_read_b128 v[202:205], v141 offset:37888
	ds_read_b128 v[206:209], v141 offset:38912
	ds_read_b128 v[210:213], v141 offset:39936
	global_load_lds_dwordx4 v[220:221], off
	v_lshl_add_u64 v[220:221], s[20:21], 0, v[130:131]
	s_mov_b32 m0, s49
	s_nop 0
	global_load_lds_dwordx4 v[220:221], off
	s_waitcnt vmcnt(8)
	s_waitcnt lgkmcnt(0)
	s_barrier
	s_setprio 1
	s_waitcnt lgkmcnt(0)
	v_mfma_f32_16x16x32_bf16 v[124:127], v[142:145], v[174:177], v[124:127]
	v_mfma_f32_16x16x32_bf16 v[120:123], v[150:153], v[174:177], v[120:123]
	v_mfma_f32_16x16x32_bf16 v[116:119], v[142:145], v[182:185], v[116:119]
	v_mfma_f32_16x16x32_bf16 v[112:115], v[150:153], v[182:185], v[112:115]
	v_mfma_f32_16x16x32_bf16 v[100:103], v[142:145], v[198:201], v[100:103]
	v_mfma_f32_16x16x32_bf16 v[96:99], v[150:153], v[198:201], v[96:99]
	v_mfma_f32_16x16x32_bf16 v[84:87], v[142:145], v[206:209], v[84:87]
	v_mfma_f32_16x16x32_bf16 v[80:83], v[150:153], v[206:209], v[80:83]
	v_mfma_f32_16x16x32_bf16 v[124:127], v[146:149], v[178:181], v[124:127]
	v_mfma_f32_16x16x32_bf16 v[120:123], v[154:157], v[178:181], v[120:123]
	v_mfma_f32_16x16x32_bf16 v[116:119], v[146:149], v[186:189], v[116:119]
	v_mfma_f32_16x16x32_bf16 v[112:115], v[154:157], v[186:189], v[112:115]
	v_mfma_f32_16x16x32_bf16 v[100:103], v[146:149], v[202:205], v[100:103]
	v_mfma_f32_16x16x32_bf16 v[96:99], v[154:157], v[202:205], v[96:99]
	v_mfma_f32_16x16x32_bf16 v[84:87], v[146:149], v[210:213], v[84:87]
	v_mfma_f32_16x16x32_bf16 v[80:83], v[154:157], v[210:213], v[80:83]
	s_setprio 0
	s_setprio 1
	v_mfma_f32_16x16x32_bf16 v[108:111], v[158:161], v[174:177], v[108:111]
	v_mfma_f32_16x16x32_bf16 v[104:107], v[166:169], v[174:177], v[104:107]
	v_mfma_f32_16x16x32_bf16 v[92:95], v[158:161], v[182:185], v[92:95]
	v_mfma_f32_16x16x32_bf16 v[88:91], v[166:169], v[182:185], v[88:91]
	v_mfma_f32_16x16x32_bf16 v[76:79], v[158:161], v[198:201], v[76:79]
	v_mfma_f32_16x16x32_bf16 v[72:75], v[166:169], v[198:201], v[72:75]
	v_mfma_f32_16x16x32_bf16 v[68:71], v[158:161], v[206:209], v[68:71]
	v_mfma_f32_16x16x32_bf16 v[64:67], v[166:169], v[206:209], v[64:67]
	v_mfma_f32_16x16x32_bf16 v[108:111], v[162:165], v[178:181], v[108:111]
	v_mfma_f32_16x16x32_bf16 v[104:107], v[170:173], v[178:181], v[104:107]
	v_mfma_f32_16x16x32_bf16 v[92:95], v[162:165], v[186:189], v[92:95]
	v_mfma_f32_16x16x32_bf16 v[88:91], v[170:173], v[186:189], v[88:91]
	v_mfma_f32_16x16x32_bf16 v[76:79], v[162:165], v[202:205], v[76:79]
	v_mfma_f32_16x16x32_bf16 v[72:75], v[170:173], v[202:205], v[72:75]
	v_mfma_f32_16x16x32_bf16 v[68:71], v[162:165], v[210:213], v[68:71]
	v_mfma_f32_16x16x32_bf16 v[64:67], v[170:173], v[210:213], v[64:67]
	s_setprio 0
	s_barrier
; #define PG8_STAGE(bufoff, gbase, voff) do { _Pragma("unroll") for (int _i = 0; _i < 2; ++_i) \
;         __builtin_amdgcn_global_load_lds((const unsigned*)((const char*)(gbase) + (voff)[_i]), (LAS unsigned*)(lds + (bufoff) + ldsw + _i * 8192), 16, 0, 0); } while (0)
; #define PG8_LDA(dst, b, h) do { _Pragma("unroll") for (int m = 0; m < 4; ++m) _Pragma("unroll") for (int k = 0; k < 2; ++k) dst[m][k] = *(const LAS bf16x8*)(lds + PG8_SA(b, h) + aoff + m * 2048 + k * 1024); } while (0)
; #define PG8_MMA(ai, bj, At, Bt) do { __builtin_amdgcn_s_setprio(1); _Pragma("unroll") for (int m = 0; m < 4; ++m) _Pragma("unroll") for (int n = 0; n < 2; ++n) _Pragma("unroll") for (int k = 0; k < 2; ++k) \
;         acc[ai][bj][m][n] = __builtin_amdgcn_mfma_f32_16x16x32_bf16(Bt[n][k], At[m][k], acc[ai][bj][m][n], 0, 0, 0); __builtin_amdgcn_s_setprio(0); } while (0)
; #define PG8_WAIT_V(n) asm volatile("s_waitcnt vmcnt(" #n ")" ::: "memory")
; #define PG8_WAIT_L(n) asm volatile("s_waitcnt lgkmcnt(" #n ")" ::: "memory")
; #define PG8_BAR __builtin_amdgcn_s_barrier()
; #define PG8_SCHED __builtin_amdgcn_sched_barrier(0)
; template <class Epi, class Sched, bool ALIGN_EPI, bool SP2, bool PERMA = false>
; __device__ __forceinline__ void gemm_phase(LAS unsigned char* lds, const int tid, const int lda, const int ldb, const Sched& S, const Epi& E) {
;     ...
;             PG8_LDA(At, 1, 1); PG8_STAGE(PG8_SB(1, 0), b3, voffB); PG8_STAGE(PG8_SB(1, 1), b3 + hsB, voffB); PG8_STAGE(PG8_SA(1, 0), a3, voffA);
;             PG8_WAIT_V(8); PG8_WAIT_L(0); PG8_BAR; PG8_MMA(1, 0, At, B0); PG8_MMA(1, 1, At, B1); PG8_BAR; PG8_SCHED;
	s_add_i32 s20, s60, s30
	v_lshl_add_u64 v[190:191], v[190:191], 0, s[54:55]
	s_mov_b32 m0, s20
	ds_read_b128 v[174:177], v141 offset:49152
	ds_read_b128 v[178:181], v141 offset:50176
	ds_read_b128 v[182:185], v141 offset:51200
	ds_read_b128 v[186:189], v141 offset:52224
	ds_read_b128 v[198:201], v141 offset:53248
	ds_read_b128 v[202:205], v141 offset:54272
	ds_read_b128 v[206:209], v141 offset:55296
	ds_read_b128 v[210:213], v141 offset:56320
	global_load_lds_dwordx4 v[190:191], off
	s_add_i32 m0, s20, 0x2000
	s_add_u32 s20, s26, 0x20080
	v_lshl_add_u64 v[190:191], v[214:215], 0, s[54:55]
	s_addc_u32 s21, s27, 0
	s_add_i32 s26, s61, s30
	global_load_lds_dwordx4 v[190:191], off
	v_lshl_add_u64 v[190:191], s[20:21], 0, v[192:193]
	s_mov_b32 m0, s26
	s_nop 0
	global_load_lds_dwordx4 v[190:191], off
	v_lshl_add_u64 v[190:191], s[20:21], 0, v[128:129]
	s_add_i32 m0, s26, 0x2000
	s_nop 0
	global_load_lds_dwordx4 v[190:191], off
	v_lshl_add_u64 v[190:191], v[216:217], 0, s[54:55]
	s_mov_b32 m0, s92
	s_nop 0
	global_load_lds_dwordx4 v[190:191], off
	v_lshl_add_u64 v[190:191], v[218:219], 0, s[54:55]
	s_mov_b32 m0, s94
	s_nop 0
	global_load_lds_dwordx4 v[190:191], off
	s_waitcnt vmcnt(8)
	s_waitcnt lgkmcnt(0)
	s_barrier
	s_setprio 1
	s_waitcnt lgkmcnt(0)
	v_mfma_f32_16x16x32_bf16 v[60:63], v[142:145], v[174:177], v[60:63]
	v_mfma_f32_16x16x32_bf16 v[56:59], v[150:153], v[174:177], v[56:59]
	v_mfma_f32_16x16x32_bf16 v[52:55], v[142:145], v[182:185], v[52:55]
	v_mfma_f32_16x16x32_bf16 v[48:51], v[150:153], v[182:185], v[48:51]
	v_mfma_f32_16x16x32_bf16 v[36:39], v[142:145], v[198:201], v[36:39]
	v_mfma_f32_16x16x32_bf16 v[32:35], v[150:153], v[198:201], v[32:35]
	v_mfma_f32_16x16x32_bf16 v[20:23], v[142:145], v[206:209], v[20:23]
	v_mfma_f32_16x16x32_bf16 v[16:19], v[150:153], v[206:209], v[16:19]
	v_mfma_f32_16x16x32_bf16 v[60:63], v[146:149], v[178:181], v[60:63]
	v_mfma_f32_16x16x32_bf16 v[56:59], v[154:157], v[178:181], v[56:59]
	v_mfma_f32_16x16x32_bf16 v[52:55], v[146:149], v[186:189], v[52:55]
	v_mfma_f32_16x16x32_bf16 v[48:51], v[154:157], v[186:189], v[48:51]
	v_mfma_f32_16x16x32_bf16 v[36:39], v[146:149], v[202:205], v[36:39]
	v_mfma_f32_16x16x32_bf16 v[32:35], v[154:157], v[202:205], v[32:35]
	v_mfma_f32_16x16x32_bf16 v[20:23], v[146:149], v[210:213], v[20:23]
	v_mfma_f32_16x16x32_bf16 v[16:19], v[154:157], v[210:213], v[16:19]
	s_setprio 0
	s_setprio 1
	v_mfma_f32_16x16x32_bf16 v[44:47], v[158:161], v[174:177], v[44:47]
	v_mfma_f32_16x16x32_bf16 v[40:43], v[166:169], v[174:177], v[40:43]
	v_mfma_f32_16x16x32_bf16 v[28:31], v[158:161], v[182:185], v[28:31]
	v_mfma_f32_16x16x32_bf16 v[24:27], v[166:169], v[182:185], v[24:27]
	v_mfma_f32_16x16x32_bf16 v[12:15], v[158:161], v[198:201], v[12:15]
	v_mfma_f32_16x16x32_bf16 v[8:11], v[166:169], v[198:201], v[8:11]
	v_mfma_f32_16x16x32_bf16 v[4:7], v[158:161], v[206:209], v[4:7]
	v_mfma_f32_16x16x32_bf16 v[0:3], v[166:169], v[206:209], v[0:3]
	v_mfma_f32_16x16x32_bf16 v[44:47], v[162:165], v[178:181], v[44:47]
	v_mfma_f32_16x16x32_bf16 v[40:43], v[170:173], v[178:181], v[40:43]
	v_mfma_f32_16x16x32_bf16 v[28:31], v[162:165], v[186:189], v[28:31]
	v_mfma_f32_16x16x32_bf16 v[24:27], v[170:173], v[186:189], v[24:27]
	v_mfma_f32_16x16x32_bf16 v[12:15], v[162:165], v[202:205], v[12:15]
	v_mfma_f32_16x16x32_bf16 v[8:11], v[170:173], v[202:205], v[8:11]
	v_mfma_f32_16x16x32_bf16 v[4:7], v[162:165], v[210:213], v[4:7]
	v_mfma_f32_16x16x32_bf16 v[0:3], v[170:173], v[210:213], v[0:3]
	s_setprio 0
	s_barrier
	s_add_i32 s33, s33, 2
	s_add_u32 s1, s1, 0x100
	s_addc_u32 s13, s13, 0
	s_cmp_gt_u32 s33, 5
	s_mov_b64 s[20:21], s[24:25]
	s_cbranch_scc1 .Lgemm6_kdone
